# K-loop barrier handoff trimmed: setprio 1 before pre-MFMA barrier, redundant lgkmcnt(0) removed, mid setprio pair removed, post barrier before setprio 0
# baseline (speedup 1.0000x reference)
; #define PG8_STAGE(bufoff, gbase, voff) do { _Pragma("unroll") for (int _i = 0; _i < 2; ++_i) \
;         __builtin_amdgcn_global_load_lds((const unsigned*)((const char*)(gbase) + (voff)[_i]), (PG8_LAS unsigned*)(lds + (bufoff) + ldsw + _i * 8192), 16, 0, 0); } while (0)
; #define PG8_LDA(dst, b, h) do { _Pragma("unroll") for (int m = 0; m < 4; ++m) _Pragma("unroll") for (int k = 0; k < 2; ++k) dst[m][k] = *(const PG8_LAS bf16x8*)(lds + PG8_SA(b, h) + aoff + m * 2048 + k * 1024); } while (0)
; #define PG8_LDB(dst, b, h) do { _Pragma("unroll") for (int n = 0; n < 2; ++n) _Pragma("unroll") for (int k = 0; k < 2; ++k) dst[n][k] = *(const PG8_LAS bf16x8*)(lds + PG8_SB(b, h) + boff + n * 2048 + k * 1024); } while (0)
; #define PG8_MMA(ai, bj, At, Bt) do { __builtin_amdgcn_s_setprio(1); _Pragma("unroll") for (int m = 0; m < 4; ++m) _Pragma("unroll") for (int n = 0; n < 2; ++n) _Pragma("unroll") for (int k = 0; k < 2; ++k) \
;         mma1<I8>(acc[ai][bj][m][n], Bt[n][k], At[m][k]); __builtin_amdgcn_s_setprio(0); } while (0)
; #define PG8_WAIT_V(n) asm volatile("s_waitcnt vmcnt(" #n ")" ::: "memory")
; #define PG8_WAIT_L(n) asm volatile("s_waitcnt lgkmcnt(" #n ")" ::: "memory")
; #define PG8_BAR __builtin_amdgcn_s_barrier()
; #define PG8_SCHED __builtin_amdgcn_sched_barrier(0)
; template <class Epi, class Sched, bool ALIGN_EPI = false, bool SP2 = false, bool I8 = false>
; __device__ __forceinline__ void gemm_phase(PG8_LAS unsigned char* lds, const Gemm g, const Sched& S, const Epi& E, const int tid) {
;     ...
;         for (int t = 0; t < nt; t += 2) {
;             const bool last = (t == nt - 2);
;             const char* a1 = cA + (size_t)(t + 1) * kstep;
;             const char* a2 = last ? nA : cA + (size_t)(t + 2) * kstep; const char* b2 = last ? nB : cB + (size_t)(t + 2) * kstep;
;             const char* a3 = a2 + kstep; const char* b3 = b2 + kstep;
;             if (last && has_next) S.a_ready(nxt);
;             if constexpr (SP2) {
;             PG8_LDB(B0, 0, 0); PG8_LDB(B1, 0, 1); PG8_SCHED; PG8_LDA(At, 0, 0); PG8_STAGE(PG8_SA(1, 1), a1 + hstepA, voffA);
;             PG8_WAIT_V(8); PG8_WAIT_L(0); PG8_BAR; PG8_MMA(0, 0, At, B0); PG8_MMA(0, 1, At, B1); PG8_BAR; PG8_SCHED;
;             PG8_LDA(At, 0, 1); PG8_STAGE(PG8_SB(0, 0), b2, voffB); PG8_STAGE(PG8_SB(0, 1), b2 + hstepB, voffB); PG8_STAGE(PG8_SA(0, 0), a2, voffA);
.LBB0_270:
	s_add_u32 s40, s38, 0xfff00080
	s_addc_u32 s41, s39, -1
	s_add_i32 s88, 0, 0x10000
	s_cmp_eq_u32 s87, 60
	s_cselect_b32 s47, s11, s41
	s_cselect_b32 s46, s29, s40
	s_cselect_b32 s41, s27, s86
	s_cselect_b32 s40, s80, s85
	s_add_i32 s90, 0, 0x14000
	v_add_u32_e32 v156, s88, v141
	v_add_u32_e32 v172, s90, v141
	ds_read_b128 v[144:147], v156
	ds_read_b128 v[148:151], v156 offset:1024
	ds_read_b128 v[152:155], v156 offset:2048
	ds_read_b128 v[156:159], v156 offset:3072
	ds_read_b128 v[160:163], v172
	ds_read_b128 v[164:167], v172 offset:1024
	ds_read_b128 v[168:171], v172 offset:2048
	ds_read_b128 v[172:175], v172 offset:3072
	v_lshl_add_u64 v[212:213], s[38:39], 0, v[138:139]
	s_add_i32 m0, s13, 0xc000
	ds_read_b128 v[176:179], v143
	ds_read_b128 v[180:183], v143 offset:1024
	ds_read_b128 v[184:187], v143 offset:2048
	ds_read_b128 v[188:191], v143 offset:3072
	ds_read_b128 v[192:195], v143 offset:4096
	ds_read_b128 v[200:203], v143 offset:5120
	ds_read_b128 v[204:207], v143 offset:6144
	ds_read_b128 v[208:211], v143 offset:7168
	global_load_lds_dwordx4 v[212:213], off
	v_lshl_add_u64 v[212:213], s[38:39], 0, v[136:137]
	s_add_i32 m0, s13, 0xe000
	s_nop 0
	global_load_lds_dwordx4 v[212:213], off
	s_waitcnt vmcnt(8)
	s_waitcnt lgkmcnt(0)
	s_setprio 1
	s_barrier
	v_mfma_f32_16x16x32_bf16 v[126:129], v[144:147], v[176:179], v[126:129]
	v_mfma_f32_16x16x32_bf16 v[122:125], v[152:155], v[176:179], v[122:125]
	v_mfma_f32_16x16x32_bf16 v[118:121], v[144:147], v[184:187], v[118:121]
	v_mfma_f32_16x16x32_bf16 v[114:117], v[152:155], v[184:187], v[114:117]
	v_mfma_f32_16x16x32_bf16 v[102:105], v[144:147], v[192:195], v[102:105]
	v_mfma_f32_16x16x32_bf16 v[98:101], v[152:155], v[192:195], v[98:101]
	v_mfma_f32_16x16x32_bf16 v[84:87], v[144:147], v[204:207], v[84:87]
	v_mfma_f32_16x16x32_bf16 v[80:83], v[152:155], v[204:207], v[80:83]
	v_mfma_f32_16x16x32_bf16 v[126:129], v[148:151], v[180:183], v[126:129]
	v_mfma_f32_16x16x32_bf16 v[122:125], v[156:159], v[180:183], v[122:125]
	v_mfma_f32_16x16x32_bf16 v[118:121], v[148:151], v[188:191], v[118:121]
	v_mfma_f32_16x16x32_bf16 v[114:117], v[156:159], v[188:191], v[114:117]
	v_mfma_f32_16x16x32_bf16 v[102:105], v[148:151], v[200:203], v[102:105]
	v_mfma_f32_16x16x32_bf16 v[98:101], v[156:159], v[200:203], v[98:101]
	v_mfma_f32_16x16x32_bf16 v[84:87], v[148:151], v[208:211], v[84:87]
	v_mfma_f32_16x16x32_bf16 v[80:83], v[156:159], v[208:211], v[80:83]
	v_mfma_f32_16x16x32_bf16 v[110:113], v[160:163], v[176:179], v[110:113]
	v_mfma_f32_16x16x32_bf16 v[106:109], v[168:171], v[176:179], v[106:109]
	v_mfma_f32_16x16x32_bf16 v[92:95], v[160:163], v[184:187], v[92:95]
	v_mfma_f32_16x16x32_bf16 v[88:91], v[168:171], v[184:187], v[88:91]
	v_mfma_f32_16x16x32_bf16 v[76:79], v[160:163], v[192:195], v[76:79]
	v_mfma_f32_16x16x32_bf16 v[72:75], v[168:171], v[192:195], v[72:75]
	v_mfma_f32_16x16x32_bf16 v[68:71], v[160:163], v[204:207], v[68:71]
	v_mfma_f32_16x16x32_bf16 v[64:67], v[168:171], v[204:207], v[64:67]
	v_mfma_f32_16x16x32_bf16 v[110:113], v[164:167], v[180:183], v[110:113]
	v_mfma_f32_16x16x32_bf16 v[106:109], v[172:175], v[180:183], v[106:109]
	v_mfma_f32_16x16x32_bf16 v[92:95], v[164:167], v[188:191], v[92:95]
	v_mfma_f32_16x16x32_bf16 v[88:91], v[172:175], v[188:191], v[88:91]
	v_mfma_f32_16x16x32_bf16 v[76:79], v[164:167], v[200:203], v[76:79]
	v_mfma_f32_16x16x32_bf16 v[72:75], v[172:175], v[200:203], v[72:75]
	v_mfma_f32_16x16x32_bf16 v[68:71], v[164:167], v[208:211], v[68:71]
	v_mfma_f32_16x16x32_bf16 v[64:67], v[172:175], v[208:211], v[64:67]
	s_barrier
	s_setprio 0
	s_add_i32 s88, s88, s59
	v_lshl_add_u64 v[212:213], s[40:41], 0, v[96:97]
	s_mov_b32 m0, s88
	ds_read_b128 v[176:179], v143 offset:16384
	ds_read_b128 v[180:183], v143 offset:17408
	ds_read_b128 v[184:187], v143 offset:18432
	ds_read_b128 v[188:191], v143 offset:19456
	ds_read_b128 v[192:195], v143 offset:20480
	ds_read_b128 v[200:203], v143 offset:21504
	ds_read_b128 v[204:207], v143 offset:22528
	ds_read_b128 v[208:211], v143 offset:23552
	global_load_lds_dwordx4 v[212:213], off
	s_add_i32 m0, s88, 0x2000
	s_add_u32 s88, s40, 0x100000
	v_lshl_add_u64 v[214:215], s[40:41], 0, v[134:135]
	s_addc_u32 s89, s41, 0
	s_add_i32 s90, s90, s59
	global_load_lds_dwordx4 v[214:215], off
	v_lshl_add_u64 v[216:217], s[88:89], 0, v[96:97]
	s_mov_b32 m0, s90
	v_lshl_add_u64 v[218:219], s[46:47], 0, v[132:133]
	global_load_lds_dwordx4 v[216:217], off
	v_lshl_add_u64 v[216:217], s[88:89], 0, v[134:135]
	s_add_i32 m0, s90, 0x2000
	s_nop 0
	global_load_lds_dwordx4 v[216:217], off
	v_lshl_add_u64 v[216:217], s[46:47], 0, v[130:131]
	s_mov_b32 m0, s13
	s_nop 0
	global_load_lds_dwordx4 v[216:217], off
	s_mov_b32 m0, s60
	s_nop 0
	global_load_lds_dwordx4 v[218:219], off
	s_waitcnt vmcnt(8)
	s_waitcnt lgkmcnt(0)
	s_setprio 1
	s_barrier
; #define PG8_STAGE(bufoff, gbase, voff) do { _Pragma("unroll") for (int _i = 0; _i < 2; ++_i) \
;         __builtin_amdgcn_global_load_lds((const unsigned*)((const char*)(gbase) + (voff)[_i]), (PG8_LAS unsigned*)(lds + (bufoff) + ldsw + _i * 8192), 16, 0, 0); } while (0)
; #define PG8_LDA(dst, b, h) do { _Pragma("unroll") for (int m = 0; m < 4; ++m) _Pragma("unroll") for (int k = 0; k < 2; ++k) dst[m][k] = *(const PG8_LAS bf16x8*)(lds + PG8_SA(b, h) + aoff + m * 2048 + k * 1024); } while (0)
; #define PG8_LDB(dst, b, h) do { _Pragma("unroll") for (int n = 0; n < 2; ++n) _Pragma("unroll") for (int k = 0; k < 2; ++k) dst[n][k] = *(const PG8_LAS bf16x8*)(lds + PG8_SB(b, h) + boff + n * 2048 + k * 1024); } while (0)
; #define PG8_MMA(ai, bj, At, Bt) do { __builtin_amdgcn_s_setprio(1); _Pragma("unroll") for (int m = 0; m < 4; ++m) _Pragma("unroll") for (int n = 0; n < 2; ++n) _Pragma("unroll") for (int k = 0; k < 2; ++k) \
;         mma1<I8>(acc[ai][bj][m][n], Bt[n][k], At[m][k]); __builtin_amdgcn_s_setprio(0); } while (0)
; #define PG8_WAIT_V(n) asm volatile("s_waitcnt vmcnt(" #n ")" ::: "memory")
; #define PG8_WAIT_L(n) asm volatile("s_waitcnt lgkmcnt(" #n ")" ::: "memory")
; #define PG8_BAR __builtin_amdgcn_s_barrier()
; #define PG8_SCHED __builtin_amdgcn_sched_barrier(0)
; template <class Epi, class Sched, bool ALIGN_EPI = false, bool SP2 = false, bool I8 = false>
; __device__ __forceinline__ void gemm_phase(PG8_LAS unsigned char* lds, const Gemm g, const Sched& S, const Epi& E, const int tid) {
;     ...
;             PG8_WAIT_V(8); PG8_WAIT_L(0); PG8_BAR; PG8_MMA(1, 0, At, B0); PG8_MMA(1, 1, At, B1); PG8_BAR; PG8_SCHED;
;             PG8_LDB(B0, 1, 0); PG8_LDB(B1, 1, 1); PG8_SCHED; PG8_LDA(At, 1, 0); PG8_STAGE(PG8_SA(0, 1), a2 + hstepA, voffA);
;             PG8_WAIT_V(8); PG8_WAIT_L(0); PG8_BAR; PG8_MMA(0, 0, At, B0); PG8_MMA(0, 1, At, B1); PG8_BAR; PG8_SCHED;
	v_mfma_f32_16x16x32_bf16 v[60:63], v[144:147], v[176:179], v[60:63]
	v_mfma_f32_16x16x32_bf16 v[56:59], v[152:155], v[176:179], v[56:59]
	v_mfma_f32_16x16x32_bf16 v[52:55], v[144:147], v[184:187], v[52:55]
	v_mfma_f32_16x16x32_bf16 v[48:51], v[152:155], v[184:187], v[48:51]
	v_mfma_f32_16x16x32_bf16 v[36:39], v[144:147], v[192:195], v[36:39]
	v_mfma_f32_16x16x32_bf16 v[32:35], v[152:155], v[192:195], v[32:35]
	v_mfma_f32_16x16x32_bf16 v[20:23], v[144:147], v[204:207], v[20:23]
	v_mfma_f32_16x16x32_bf16 v[16:19], v[152:155], v[204:207], v[16:19]
	v_mfma_f32_16x16x32_bf16 v[60:63], v[148:151], v[180:183], v[60:63]
	v_mfma_f32_16x16x32_bf16 v[56:59], v[156:159], v[180:183], v[56:59]
	v_mfma_f32_16x16x32_bf16 v[52:55], v[148:151], v[188:191], v[52:55]
	v_mfma_f32_16x16x32_bf16 v[48:51], v[156:159], v[188:191], v[48:51]
	v_mfma_f32_16x16x32_bf16 v[36:39], v[148:151], v[200:203], v[36:39]
	v_mfma_f32_16x16x32_bf16 v[32:35], v[156:159], v[200:203], v[32:35]
	v_mfma_f32_16x16x32_bf16 v[20:23], v[148:151], v[208:211], v[20:23]
	v_mfma_f32_16x16x32_bf16 v[16:19], v[156:159], v[208:211], v[16:19]
	v_mfma_f32_16x16x32_bf16 v[44:47], v[160:163], v[176:179], v[44:47]
	v_mfma_f32_16x16x32_bf16 v[40:43], v[168:171], v[176:179], v[40:43]
	v_mfma_f32_16x16x32_bf16 v[28:31], v[160:163], v[184:187], v[28:31]
	v_mfma_f32_16x16x32_bf16 v[24:27], v[168:171], v[184:187], v[24:27]
	v_mfma_f32_16x16x32_bf16 v[12:15], v[160:163], v[192:195], v[12:15]
	v_mfma_f32_16x16x32_bf16 v[8:11], v[168:171], v[192:195], v[8:11]
	v_mfma_f32_16x16x32_bf16 v[4:7], v[160:163], v[204:207], v[4:7]
	v_mfma_f32_16x16x32_bf16 v[0:3], v[168:171], v[204:207], v[0:3]
	v_mfma_f32_16x16x32_bf16 v[44:47], v[164:167], v[180:183], v[44:47]
	v_mfma_f32_16x16x32_bf16 v[40:43], v[172:175], v[180:183], v[40:43]
	v_mfma_f32_16x16x32_bf16 v[28:31], v[164:167], v[188:191], v[28:31]
	v_mfma_f32_16x16x32_bf16 v[24:27], v[172:175], v[188:191], v[24:27]
	v_mfma_f32_16x16x32_bf16 v[12:15], v[164:167], v[200:203], v[12:15]
	v_mfma_f32_16x16x32_bf16 v[8:11], v[172:175], v[200:203], v[8:11]
	v_mfma_f32_16x16x32_bf16 v[4:7], v[164:167], v[208:211], v[4:7]
	v_mfma_f32_16x16x32_bf16 v[0:3], v[172:175], v[208:211], v[0:3]
	s_barrier
	s_setprio 0
	s_add_i32 s88, 0, 0x18000
	s_add_i32 s89, 0, 0x1c000
	v_add_u32_e32 v156, s88, v141
	v_add_u32_e32 v172, s89, v141
	ds_read_b128 v[144:147], v156
	ds_read_b128 v[148:151], v156 offset:1024
	ds_read_b128 v[152:155], v156 offset:2048
	ds_read_b128 v[156:159], v156 offset:3072
	ds_read_b128 v[160:163], v172
	ds_read_b128 v[164:167], v172 offset:1024
	ds_read_b128 v[168:171], v172 offset:2048
	ds_read_b128 v[172:175], v172 offset:3072
	s_add_u32 s46, s46, 0x100000
	s_addc_u32 s47, s47, 0
	s_mov_b32 m0, s62
	v_lshl_add_u64 v[220:221], s[46:47], 0, v[130:131]
	ds_read_b128 v[176:179], v143 offset:32768
	ds_read_b128 v[180:183], v143 offset:33792
	ds_read_b128 v[184:187], v143 offset:34816
	ds_read_b128 v[188:191], v143 offset:35840
	ds_read_b128 v[192:195], v143 offset:36864
	ds_read_b128 v[200:203], v143 offset:37888
	ds_read_b128 v[204:207], v143 offset:38912
	ds_read_b128 v[208:211], v143 offset:39936
	global_load_lds_dwordx4 v[220:221], off
	v_lshl_add_u64 v[220:221], s[46:47], 0, v[132:133]
	s_mov_b32 m0, s63
	s_nop 0
	global_load_lds_dwordx4 v[220:221], off
	s_waitcnt vmcnt(8)
	s_waitcnt lgkmcnt(0)
	s_setprio 1
	s_barrier
	v_mfma_f32_16x16x32_bf16 v[126:129], v[144:147], v[176:179], v[126:129]
	v_mfma_f32_16x16x32_bf16 v[122:125], v[152:155], v[176:179], v[122:125]
	v_mfma_f32_16x16x32_bf16 v[118:121], v[144:147], v[184:187], v[118:121]
	v_mfma_f32_16x16x32_bf16 v[114:117], v[152:155], v[184:187], v[114:117]
	v_mfma_f32_16x16x32_bf16 v[102:105], v[144:147], v[192:195], v[102:105]
	v_mfma_f32_16x16x32_bf16 v[98:101], v[152:155], v[192:195], v[98:101]
	v_mfma_f32_16x16x32_bf16 v[84:87], v[144:147], v[204:207], v[84:87]
	v_mfma_f32_16x16x32_bf16 v[80:83], v[152:155], v[204:207], v[80:83]
	v_mfma_f32_16x16x32_bf16 v[126:129], v[148:151], v[180:183], v[126:129]
	v_mfma_f32_16x16x32_bf16 v[122:125], v[156:159], v[180:183], v[122:125]
	v_mfma_f32_16x16x32_bf16 v[118:121], v[148:151], v[188:191], v[118:121]
	v_mfma_f32_16x16x32_bf16 v[114:117], v[156:159], v[188:191], v[114:117]
	v_mfma_f32_16x16x32_bf16 v[102:105], v[148:151], v[200:203], v[102:105]
	v_mfma_f32_16x16x32_bf16 v[98:101], v[156:159], v[200:203], v[98:101]
	v_mfma_f32_16x16x32_bf16 v[84:87], v[148:151], v[208:211], v[84:87]
	v_mfma_f32_16x16x32_bf16 v[80:83], v[156:159], v[208:211], v[80:83]
	v_mfma_f32_16x16x32_bf16 v[110:113], v[160:163], v[176:179], v[110:113]
	v_mfma_f32_16x16x32_bf16 v[106:109], v[168:171], v[176:179], v[106:109]
	v_mfma_f32_16x16x32_bf16 v[92:95], v[160:163], v[184:187], v[92:95]
	v_mfma_f32_16x16x32_bf16 v[88:91], v[168:171], v[184:187], v[88:91]
	v_mfma_f32_16x16x32_bf16 v[76:79], v[160:163], v[192:195], v[76:79]
	v_mfma_f32_16x16x32_bf16 v[72:75], v[168:171], v[192:195], v[72:75]
	v_mfma_f32_16x16x32_bf16 v[68:71], v[160:163], v[204:207], v[68:71]
	v_mfma_f32_16x16x32_bf16 v[64:67], v[168:171], v[204:207], v[64:67]
	v_mfma_f32_16x16x32_bf16 v[110:113], v[164:167], v[180:183], v[110:113]
	v_mfma_f32_16x16x32_bf16 v[106:109], v[172:175], v[180:183], v[106:109]
	v_mfma_f32_16x16x32_bf16 v[92:95], v[164:167], v[188:191], v[92:95]
	v_mfma_f32_16x16x32_bf16 v[88:91], v[172:175], v[188:191], v[88:91]
	v_mfma_f32_16x16x32_bf16 v[76:79], v[164:167], v[200:203], v[76:79]
	v_mfma_f32_16x16x32_bf16 v[72:75], v[172:175], v[200:203], v[72:75]
	v_mfma_f32_16x16x32_bf16 v[68:71], v[164:167], v[208:211], v[68:71]
	v_mfma_f32_16x16x32_bf16 v[64:67], v[172:175], v[208:211], v[64:67]
	s_barrier
; #define PG8_STAGE(bufoff, gbase, voff) do { _Pragma("unroll") for (int _i = 0; _i < 2; ++_i) \
;         __builtin_amdgcn_global_load_lds((const unsigned*)((const char*)(gbase) + (voff)[_i]), (PG8_LAS unsigned*)(lds + (bufoff) + ldsw + _i * 8192), 16, 0, 0); } while (0)
; #define PG8_LDA(dst, b, h) do { _Pragma("unroll") for (int m = 0; m < 4; ++m) _Pragma("unroll") for (int k = 0; k < 2; ++k) dst[m][k] = *(const PG8_LAS bf16x8*)(lds + PG8_SA(b, h) + aoff + m * 2048 + k * 1024); } while (0)
; #define PG8_MMA(ai, bj, At, Bt) do { __builtin_amdgcn_s_setprio(1); _Pragma("unroll") for (int m = 0; m < 4; ++m) _Pragma("unroll") for (int n = 0; n < 2; ++n) _Pragma("unroll") for (int k = 0; k < 2; ++k) \
;         mma1<I8>(acc[ai][bj][m][n], Bt[n][k], At[m][k]); __builtin_amdgcn_s_setprio(0); } while (0)
; #define PG8_WAIT_V(n) asm volatile("s_waitcnt vmcnt(" #n ")" ::: "memory")
; #define PG8_WAIT_L(n) asm volatile("s_waitcnt lgkmcnt(" #n ")" ::: "memory")
; #define PG8_BAR __builtin_amdgcn_s_barrier()
; #define PG8_SCHED __builtin_amdgcn_sched_barrier(0)
; template <class Epi, class Sched, bool ALIGN_EPI = false, bool SP2 = false, bool I8 = false>
; __device__ __forceinline__ void gemm_phase(PG8_LAS unsigned char* lds, const Gemm g, const Sched& S, const Epi& E, const int tid) {
;     ...
;             PG8_LDA(At, 1, 1); PG8_STAGE(PG8_SB(1, 0), b3, voffB); PG8_STAGE(PG8_SB(1, 1), b3 + hstepB, voffB); PG8_STAGE(PG8_SA(1, 0), a3, voffA);
;             PG8_WAIT_V(8); PG8_WAIT_L(0); PG8_BAR; PG8_MMA(1, 0, At, B0); PG8_MMA(1, 1, At, B1); PG8_BAR; PG8_SCHED;
;     ...
;         if constexpr (ALIGN_EPI) { if (wr == 0) PG8_BAR; }
	s_setprio 0
	s_add_i32 s46, s88, s59
	v_lshl_add_u64 v[212:213], v[212:213], 0, s[42:43]
	s_mov_b32 m0, s46
	ds_read_b128 v[176:179], v143 offset:49152
	ds_read_b128 v[180:183], v143 offset:50176
	ds_read_b128 v[184:187], v143 offset:51200
	ds_read_b128 v[188:191], v143 offset:52224
	ds_read_b128 v[192:195], v143 offset:53248
	ds_read_b128 v[200:203], v143 offset:54272
	ds_read_b128 v[204:207], v143 offset:55296
	ds_read_b128 v[208:211], v143 offset:56320
	global_load_lds_dwordx4 v[212:213], off
	s_add_i32 m0, s46, 0x2000
	s_add_u32 s40, s40, 0x100080
	v_lshl_add_u64 v[212:213], v[214:215], 0, s[42:43]
	s_addc_u32 s41, s41, 0
	s_add_i32 s46, s89, s59
	global_load_lds_dwordx4 v[212:213], off
	v_lshl_add_u64 v[212:213], s[40:41], 0, v[96:97]
	s_mov_b32 m0, s46
	s_nop 0
	global_load_lds_dwordx4 v[212:213], off
	v_lshl_add_u64 v[212:213], s[40:41], 0, v[134:135]
	s_add_i32 m0, s46, 0x2000
	s_nop 0
	global_load_lds_dwordx4 v[212:213], off
	v_lshl_add_u64 v[212:213], v[216:217], 0, s[42:43]
	s_mov_b32 m0, s65
	s_nop 0
	global_load_lds_dwordx4 v[212:213], off
	v_lshl_add_u64 v[212:213], v[218:219], 0, s[42:43]
	s_mov_b32 m0, s66
	s_nop 0
	global_load_lds_dwordx4 v[212:213], off
	s_waitcnt vmcnt(8)
	s_waitcnt lgkmcnt(0)
	s_setprio 1
	s_barrier
	v_mfma_f32_16x16x32_bf16 v[60:63], v[144:147], v[176:179], v[60:63]
	v_mfma_f32_16x16x32_bf16 v[56:59], v[152:155], v[176:179], v[56:59]
	v_mfma_f32_16x16x32_bf16 v[52:55], v[144:147], v[184:187], v[52:55]
	v_mfma_f32_16x16x32_bf16 v[48:51], v[152:155], v[184:187], v[48:51]
	v_mfma_f32_16x16x32_bf16 v[36:39], v[144:147], v[192:195], v[36:39]
	v_mfma_f32_16x16x32_bf16 v[32:35], v[152:155], v[192:195], v[32:35]
	v_mfma_f32_16x16x32_bf16 v[20:23], v[144:147], v[204:207], v[20:23]
	v_mfma_f32_16x16x32_bf16 v[16:19], v[152:155], v[204:207], v[16:19]
	v_mfma_f32_16x16x32_bf16 v[60:63], v[148:151], v[180:183], v[60:63]
	v_mfma_f32_16x16x32_bf16 v[56:59], v[156:159], v[180:183], v[56:59]
	v_mfma_f32_16x16x32_bf16 v[52:55], v[148:151], v[188:191], v[52:55]
	v_mfma_f32_16x16x32_bf16 v[48:51], v[156:159], v[188:191], v[48:51]
	v_mfma_f32_16x16x32_bf16 v[36:39], v[148:151], v[200:203], v[36:39]
	v_mfma_f32_16x16x32_bf16 v[32:35], v[156:159], v[200:203], v[32:35]
	v_mfma_f32_16x16x32_bf16 v[20:23], v[148:151], v[208:211], v[20:23]
	v_mfma_f32_16x16x32_bf16 v[16:19], v[156:159], v[208:211], v[16:19]
	v_mfma_f32_16x16x32_bf16 v[44:47], v[160:163], v[176:179], v[44:47]
	v_mfma_f32_16x16x32_bf16 v[40:43], v[168:171], v[176:179], v[40:43]
	v_mfma_f32_16x16x32_bf16 v[28:31], v[160:163], v[184:187], v[28:31]
	v_mfma_f32_16x16x32_bf16 v[24:27], v[168:171], v[184:187], v[24:27]
	v_mfma_f32_16x16x32_bf16 v[12:15], v[160:163], v[192:195], v[12:15]
	v_mfma_f32_16x16x32_bf16 v[8:11], v[168:171], v[192:195], v[8:11]
	v_mfma_f32_16x16x32_bf16 v[4:7], v[160:163], v[204:207], v[4:7]
	v_mfma_f32_16x16x32_bf16 v[0:3], v[168:171], v[204:207], v[0:3]
	v_mfma_f32_16x16x32_bf16 v[44:47], v[164:167], v[180:183], v[44:47]
	v_mfma_f32_16x16x32_bf16 v[40:43], v[172:175], v[180:183], v[40:43]
	v_mfma_f32_16x16x32_bf16 v[28:31], v[164:167], v[188:191], v[28:31]
	v_mfma_f32_16x16x32_bf16 v[24:27], v[172:175], v[188:191], v[24:27]
	v_mfma_f32_16x16x32_bf16 v[12:15], v[164:167], v[200:203], v[12:15]
	v_mfma_f32_16x16x32_bf16 v[8:11], v[172:175], v[200:203], v[8:11]
	v_mfma_f32_16x16x32_bf16 v[4:7], v[164:167], v[208:211], v[4:7]
	v_mfma_f32_16x16x32_bf16 v[0:3], v[172:175], v[208:211], v[0:3]
	s_barrier
	s_setprio 0
	s_add_i32 s87, s87, 2
	s_add_u32 s85, s85, 0x100
	s_addc_u32 s86, s86, 0
	s_add_u32 s38, s38, 0x100
	s_addc_u32 s39, s39, 0
	s_cmp_gt_u32 s87, 61
	s_cbranch_scc0 .LBB0_270
	s_and_b64 vcc, exec, s[22:23]
	s_cbranch_vccz .LBB0_273
	s_barrier

; #define PG8_STAGE(bufoff, gbase, voff) do { _Pragma("unroll") for (int _i = 0; _i < 2; ++_i) \
;         __builtin_amdgcn_global_load_lds((const unsigned*)((const char*)(gbase) + (voff)[_i]), (PG8_LAS unsigned*)(lds + (bufoff) + ldsw + _i * 8192), 16, 0, 0); } while (0)
; #define PG8_LDA(dst, b, h) do { _Pragma("unroll") for (int m = 0; m < 4; ++m) _Pragma("unroll") for (int k = 0; k < 2; ++k) dst[m][k] = *(const PG8_LAS bf16x8*)(lds + PG8_SA(b, h) + aoff + m * 2048 + k * 1024); } while (0)
; #define PG8_LDB(dst, b, h) do { _Pragma("unroll") for (int n = 0; n < 2; ++n) _Pragma("unroll") for (int k = 0; k < 2; ++k) dst[n][k] = *(const PG8_LAS bf16x8*)(lds + PG8_SB(b, h) + boff + n * 2048 + k * 1024); } while (0)
; #define PG8_MMA(ai, bj, At, Bt) do { __builtin_amdgcn_s_setprio(1); _Pragma("unroll") for (int m = 0; m < 4; ++m) _Pragma("unroll") for (int n = 0; n < 2; ++n) _Pragma("unroll") for (int k = 0; k < 2; ++k) \
;         mma1<I8>(acc[ai][bj][m][n], Bt[n][k], At[m][k]); __builtin_amdgcn_s_setprio(0); } while (0)
; #define PG8_WAIT_V(n) asm volatile("s_waitcnt vmcnt(" #n ")" ::: "memory")
; #define PG8_WAIT_L(n) asm volatile("s_waitcnt lgkmcnt(" #n ")" ::: "memory")
; #define PG8_BAR __builtin_amdgcn_s_barrier()
; #define PG8_SCHED __builtin_amdgcn_sched_barrier(0)
; template <class Epi, class Sched, bool ALIGN_EPI = false, bool SP2 = false, bool I8 = false>
; __device__ __forceinline__ void gemm_phase(PG8_LAS unsigned char* lds, const Gemm g, const Sched& S, const Epi& E, const int tid) {
;     ...
;         for (int t = 0; t < nt; t += 2) {
;             const bool last = (t == nt - 2);
;             const char* a1 = cA + (size_t)(t + 1) * kstep;
;             const char* a2 = last ? nA : cA + (size_t)(t + 2) * kstep; const char* b2 = last ? nB : cB + (size_t)(t + 2) * kstep;
;             const char* a3 = a2 + kstep; const char* b3 = b2 + kstep;
;             if (last && has_next) S.a_ready(nxt);
;             if constexpr (SP2) {
;             PG8_LDB(B0, 0, 0); PG8_LDB(B1, 0, 1); PG8_SCHED; PG8_LDA(At, 0, 0); PG8_STAGE(PG8_SA(1, 1), a1 + hstepA, voffA);
;             PG8_WAIT_V(8); PG8_WAIT_L(0); PG8_BAR; PG8_MMA(0, 0, At, B0); PG8_MMA(0, 1, At, B1); PG8_BAR; PG8_SCHED;
;             PG8_LDA(At, 0, 1); PG8_STAGE(PG8_SB(0, 0), b2, voffB); PG8_STAGE(PG8_SB(0, 1), b2 + hstepB, voffB); PG8_STAGE(PG8_SA(0, 0), a2, voffA);
.LBB0_335:
	s_add_u32 s54, s46, 0xfff80080
	s_addc_u32 s55, s47, -1
	s_add_i32 s70, 0, 0x10000
	s_cmp_eq_u32 s65, 28
	s_cselect_b32 s57, s5, s55
	s_cselect_b32 s56, s31, s54
	s_cselect_b32 s55, s13, s60
	s_cselect_b32 s54, s41, s49
	s_add_i32 s87, 0, 0x14000
	v_add_u32_e32 v68, s70, v187
	v_add_u32_e32 v168, s87, v187
	ds_read_b128 v[48:51], v68
	ds_read_b128 v[52:55], v68 offset:1024
	ds_read_b128 v[64:67], v68 offset:2048
	ds_read_b128 v[68:71], v68 offset:3072
	ds_read_b128 v[156:159], v168
	ds_read_b128 v[160:163], v168 offset:1024
	ds_read_b128 v[164:167], v168 offset:2048
	ds_read_b128 v[168:171], v168 offset:3072
	v_lshl_add_u64 v[184:185], s[46:47], 0, v[154:155]
	s_add_i32 m0, s80, 0xc000
	ds_read_b128 v[172:175], v189
	ds_read_b128 v[176:179], v189 offset:1024
	ds_read_b128 v[180:183], v189 offset:2048
	ds_read_b128 v[190:193], v189 offset:3072
	ds_read_b128 v[200:203], v189 offset:4096
	ds_read_b128 v[204:207], v189 offset:5120
	ds_read_b128 v[208:211], v189 offset:6144
	ds_read_b128 v[212:215], v189 offset:7168
	global_load_lds_dwordx4 v[184:185], off
	v_lshl_add_u64 v[184:185], s[46:47], 0, v[152:153]
	s_add_i32 m0, s80, 0xe000
	s_nop 0
	global_load_lds_dwordx4 v[184:185], off
	s_waitcnt vmcnt(8)
	s_waitcnt lgkmcnt(0)
	s_setprio 1
	s_barrier
	v_mfma_i32_16x16x64_i8 v[142:145], v[48:51], v[172:175], v[142:145]
	v_mfma_i32_16x16x64_i8 v[138:141], v[64:67], v[172:175], v[138:141]
	v_mfma_i32_16x16x64_i8 v[126:129], v[48:51], v[180:183], v[126:129]
	v_mfma_i32_16x16x64_i8 v[122:125], v[64:67], v[180:183], v[122:125]
	v_mfma_i32_16x16x64_i8 v[110:113], v[48:51], v[200:203], v[110:113]
	v_mfma_i32_16x16x64_i8 v[106:109], v[64:67], v[200:203], v[106:109]
	v_mfma_i32_16x16x64_i8 v[92:95], v[48:51], v[208:211], v[92:95]
	v_mfma_i32_16x16x64_i8 v[88:91], v[64:67], v[208:211], v[88:91]
	v_mfma_i32_16x16x64_i8 v[142:145], v[52:55], v[176:179], v[142:145]
	v_mfma_i32_16x16x64_i8 v[138:141], v[68:71], v[176:179], v[138:141]
	v_mfma_i32_16x16x64_i8 v[126:129], v[52:55], v[190:193], v[126:129]
	v_mfma_i32_16x16x64_i8 v[122:125], v[68:71], v[190:193], v[122:125]
	v_mfma_i32_16x16x64_i8 v[110:113], v[52:55], v[204:207], v[110:113]
	v_mfma_i32_16x16x64_i8 v[106:109], v[68:71], v[204:207], v[106:109]
	v_mfma_i32_16x16x64_i8 v[92:95], v[52:55], v[212:215], v[92:95]
	v_mfma_i32_16x16x64_i8 v[88:91], v[68:71], v[212:215], v[88:91]
	v_mfma_i32_16x16x64_i8 v[134:137], v[156:159], v[172:175], v[134:137]
	v_mfma_i32_16x16x64_i8 v[130:133], v[164:167], v[172:175], v[130:133]
	v_mfma_i32_16x16x64_i8 v[118:121], v[156:159], v[180:183], v[118:121]
	v_mfma_i32_16x16x64_i8 v[114:117], v[164:167], v[180:183], v[114:117]
	v_mfma_i32_16x16x64_i8 v[102:105], v[156:159], v[200:203], v[102:105]
	v_mfma_i32_16x16x64_i8 v[98:101], v[164:167], v[200:203], v[98:101]
	v_mfma_i32_16x16x64_i8 v[84:87], v[156:159], v[208:211], v[84:87]
	v_mfma_i32_16x16x64_i8 v[80:83], v[164:167], v[208:211], v[80:83]
	v_mfma_i32_16x16x64_i8 v[134:137], v[160:163], v[176:179], v[134:137]
	v_mfma_i32_16x16x64_i8 v[130:133], v[168:171], v[176:179], v[130:133]
	v_mfma_i32_16x16x64_i8 v[118:121], v[160:163], v[190:193], v[118:121]
	v_mfma_i32_16x16x64_i8 v[114:117], v[168:171], v[190:193], v[114:117]
	v_mfma_i32_16x16x64_i8 v[102:105], v[160:163], v[204:207], v[102:105]
	v_mfma_i32_16x16x64_i8 v[98:101], v[168:171], v[204:207], v[98:101]
	v_mfma_i32_16x16x64_i8 v[84:87], v[160:163], v[212:215], v[84:87]
	v_mfma_i32_16x16x64_i8 v[80:83], v[168:171], v[212:215], v[80:83]
	s_barrier
	s_setprio 0
	s_add_i32 s70, s70, s75
	v_lshl_add_u64 v[184:185], s[54:55], 0, v[96:97]
	s_mov_b32 m0, s70
	ds_read_b128 v[172:175], v189 offset:16384
	ds_read_b128 v[176:179], v189 offset:17408
	ds_read_b128 v[180:183], v189 offset:18432
	ds_read_b128 v[190:193], v189 offset:19456
	ds_read_b128 v[200:203], v189 offset:20480
	ds_read_b128 v[204:207], v189 offset:21504
	ds_read_b128 v[208:211], v189 offset:22528
	ds_read_b128 v[212:215], v189 offset:23552
	global_load_lds_dwordx4 v[184:185], off
	s_add_i32 m0, s70, 0x2000
	s_add_u32 s76, s54, 0x80000
	v_lshl_add_u64 v[194:195], s[54:55], 0, v[150:151]
	s_addc_u32 s77, s55, 0
	s_add_i32 s70, s87, s75
	global_load_lds_dwordx4 v[194:195], off
	v_lshl_add_u64 v[216:217], s[76:77], 0, v[96:97]
	s_mov_b32 m0, s70
	v_lshl_add_u64 v[218:219], s[56:57], 0, v[148:149]
	global_load_lds_dwordx4 v[216:217], off
	v_lshl_add_u64 v[216:217], s[76:77], 0, v[150:151]
	s_add_i32 m0, s70, 0x2000
	s_nop 0
	global_load_lds_dwordx4 v[216:217], off
	v_lshl_add_u64 v[216:217], s[56:57], 0, v[146:147]
	s_mov_b32 m0, s80
	s_nop 0
	global_load_lds_dwordx4 v[216:217], off
	s_mov_b32 m0, s85
	s_nop 0
	global_load_lds_dwordx4 v[218:219], off
	s_waitcnt vmcnt(8)
	s_waitcnt lgkmcnt(0)
	s_setprio 1
	s_barrier
; #define PG8_STAGE(bufoff, gbase, voff) do { _Pragma("unroll") for (int _i = 0; _i < 2; ++_i) \
;         __builtin_amdgcn_global_load_lds((const unsigned*)((const char*)(gbase) + (voff)[_i]), (PG8_LAS unsigned*)(lds + (bufoff) + ldsw + _i * 8192), 16, 0, 0); } while (0)
; #define PG8_LDA(dst, b, h) do { _Pragma("unroll") for (int m = 0; m < 4; ++m) _Pragma("unroll") for (int k = 0; k < 2; ++k) dst[m][k] = *(const PG8_LAS bf16x8*)(lds + PG8_SA(b, h) + aoff + m * 2048 + k * 1024); } while (0)
; #define PG8_LDB(dst, b, h) do { _Pragma("unroll") for (int n = 0; n < 2; ++n) _Pragma("unroll") for (int k = 0; k < 2; ++k) dst[n][k] = *(const PG8_LAS bf16x8*)(lds + PG8_SB(b, h) + boff + n * 2048 + k * 1024); } while (0)
; #define PG8_MMA(ai, bj, At, Bt) do { __builtin_amdgcn_s_setprio(1); _Pragma("unroll") for (int m = 0; m < 4; ++m) _Pragma("unroll") for (int n = 0; n < 2; ++n) _Pragma("unroll") for (int k = 0; k < 2; ++k) \
;         mma1<I8>(acc[ai][bj][m][n], Bt[n][k], At[m][k]); __builtin_amdgcn_s_setprio(0); } while (0)
; #define PG8_WAIT_V(n) asm volatile("s_waitcnt vmcnt(" #n ")" ::: "memory")
; #define PG8_WAIT_L(n) asm volatile("s_waitcnt lgkmcnt(" #n ")" ::: "memory")
; #define PG8_BAR __builtin_amdgcn_s_barrier()
; #define PG8_SCHED __builtin_amdgcn_sched_barrier(0)
; template <class Epi, class Sched, bool ALIGN_EPI = false, bool SP2 = false, bool I8 = false>
; __device__ __forceinline__ void gemm_phase(PG8_LAS unsigned char* lds, const Gemm g, const Sched& S, const Epi& E, const int tid) {
;     ...
;             PG8_WAIT_V(8); PG8_WAIT_L(0); PG8_BAR; PG8_MMA(1, 0, At, B0); PG8_MMA(1, 1, At, B1); PG8_BAR; PG8_SCHED;
;             PG8_LDB(B0, 1, 0); PG8_LDB(B1, 1, 1); PG8_SCHED; PG8_LDA(At, 1, 0); PG8_STAGE(PG8_SA(0, 1), a2 + hstepA, voffA);
;             PG8_WAIT_V(8); PG8_WAIT_L(0); PG8_BAR; PG8_MMA(0, 0, At, B0); PG8_MMA(0, 1, At, B1); PG8_BAR; PG8_SCHED;
	v_mfma_i32_16x16x64_i8 v[76:79], v[48:51], v[172:175], v[76:79]
	v_mfma_i32_16x16x64_i8 v[72:75], v[64:67], v[172:175], v[72:75]
	v_mfma_i32_16x16x64_i8 v[44:47], v[48:51], v[180:183], v[44:47]
	v_mfma_i32_16x16x64_i8 v[40:43], v[64:67], v[180:183], v[40:43]
	v_mfma_i32_16x16x64_i8 v[28:31], v[48:51], v[200:203], v[28:31]
	v_mfma_i32_16x16x64_i8 v[24:27], v[64:67], v[200:203], v[24:27]
	v_mfma_i32_16x16x64_i8 v[12:15], v[48:51], v[208:211], v[12:15]
	v_mfma_i32_16x16x64_i8 v[8:11], v[64:67], v[208:211], v[8:11]
	v_mfma_i32_16x16x64_i8 v[76:79], v[52:55], v[176:179], v[76:79]
	v_mfma_i32_16x16x64_i8 v[72:75], v[68:71], v[176:179], v[72:75]
	v_mfma_i32_16x16x64_i8 v[44:47], v[52:55], v[190:193], v[44:47]
	v_mfma_i32_16x16x64_i8 v[40:43], v[68:71], v[190:193], v[40:43]
	v_mfma_i32_16x16x64_i8 v[28:31], v[52:55], v[204:207], v[28:31]
	v_mfma_i32_16x16x64_i8 v[24:27], v[68:71], v[204:207], v[24:27]
	v_mfma_i32_16x16x64_i8 v[12:15], v[52:55], v[212:215], v[12:15]
	v_mfma_i32_16x16x64_i8 v[8:11], v[68:71], v[212:215], v[8:11]
	v_mfma_i32_16x16x64_i8 v[36:39], v[156:159], v[180:183], v[36:39]
	v_mfma_i32_16x16x64_i8 v[32:35], v[164:167], v[180:183], v[32:35]
	v_mfma_i32_16x16x64_i8 v[20:23], v[156:159], v[200:203], v[20:23]
	v_mfma_i32_16x16x64_i8 v[16:19], v[164:167], v[200:203], v[16:19]
	v_mfma_i32_16x16x64_i8 v[4:7], v[156:159], v[208:211], v[4:7]
	v_mfma_i32_16x16x64_i8 v[0:3], v[164:167], v[208:211], v[0:3]
	v_mfma_i32_16x16x64_i8 v[48:51], v[156:159], v[172:175], v[60:63]
	v_mfma_i32_16x16x64_i8 v[52:55], v[164:167], v[172:175], v[56:59]
	v_mfma_i32_16x16x64_i8 v[36:39], v[160:163], v[190:193], v[36:39]
	v_mfma_i32_16x16x64_i8 v[32:35], v[168:171], v[190:193], v[32:35]
	v_mfma_i32_16x16x64_i8 v[20:23], v[160:163], v[204:207], v[20:23]
	v_mfma_i32_16x16x64_i8 v[16:19], v[168:171], v[204:207], v[16:19]
	v_mfma_i32_16x16x64_i8 v[4:7], v[160:163], v[212:215], v[4:7]
	v_mfma_i32_16x16x64_i8 v[0:3], v[168:171], v[212:215], v[0:3]
	v_mfma_i32_16x16x64_i8 v[48:51], v[160:163], v[176:179], v[48:51]
	v_mfma_i32_16x16x64_i8 v[52:55], v[168:171], v[176:179], v[52:55]
	s_barrier
	s_setprio 0
	s_add_i32 s70, 0, 0x18000
	s_add_i32 s76, 0, 0x1c000
	v_add_u32_e32 v68, s70, v187
	v_add_u32_e32 v168, s76, v187
	ds_read_b128 v[56:59], v68
	ds_read_b128 v[60:63], v68 offset:1024
	ds_read_b128 v[64:67], v68 offset:2048
	ds_read_b128 v[68:71], v68 offset:3072
	ds_read_b128 v[156:159], v168
	ds_read_b128 v[160:163], v168 offset:1024
	ds_read_b128 v[164:167], v168 offset:2048
	ds_read_b128 v[168:171], v168 offset:3072
	s_add_u32 s56, s56, 0x80000
	s_addc_u32 s57, s57, 0
	s_mov_b32 m0, s86
	v_lshl_add_u64 v[220:221], s[56:57], 0, v[146:147]
	ds_read_b128 v[172:175], v189 offset:32768
	ds_read_b128 v[176:179], v189 offset:33792
	ds_read_b128 v[180:183], v189 offset:34816
	ds_read_b128 v[190:193], v189 offset:35840
	ds_read_b128 v[200:203], v189 offset:36864
	ds_read_b128 v[204:207], v189 offset:37888
	ds_read_b128 v[208:211], v189 offset:38912
	ds_read_b128 v[212:215], v189 offset:39936
	global_load_lds_dwordx4 v[220:221], off
	v_lshl_add_u64 v[220:221], s[56:57], 0, v[148:149]
	s_mov_b32 m0, s88
	s_nop 0
	global_load_lds_dwordx4 v[220:221], off
	s_waitcnt vmcnt(8)
	s_waitcnt lgkmcnt(0)
	s_setprio 1
	s_barrier
	v_mfma_i32_16x16x64_i8 v[142:145], v[56:59], v[172:175], v[142:145]
	v_mfma_i32_16x16x64_i8 v[138:141], v[64:67], v[172:175], v[138:141]
	v_mfma_i32_16x16x64_i8 v[126:129], v[56:59], v[180:183], v[126:129]
	v_mfma_i32_16x16x64_i8 v[122:125], v[64:67], v[180:183], v[122:125]
	v_mfma_i32_16x16x64_i8 v[110:113], v[56:59], v[200:203], v[110:113]
	v_mfma_i32_16x16x64_i8 v[106:109], v[64:67], v[200:203], v[106:109]
	v_mfma_i32_16x16x64_i8 v[92:95], v[56:59], v[208:211], v[92:95]
	v_mfma_i32_16x16x64_i8 v[88:91], v[64:67], v[208:211], v[88:91]
	v_mfma_i32_16x16x64_i8 v[142:145], v[60:63], v[176:179], v[142:145]
	v_mfma_i32_16x16x64_i8 v[138:141], v[68:71], v[176:179], v[138:141]
	v_mfma_i32_16x16x64_i8 v[126:129], v[60:63], v[190:193], v[126:129]
	v_mfma_i32_16x16x64_i8 v[122:125], v[68:71], v[190:193], v[122:125]
	v_mfma_i32_16x16x64_i8 v[110:113], v[60:63], v[204:207], v[110:113]
	v_mfma_i32_16x16x64_i8 v[106:109], v[68:71], v[204:207], v[106:109]
	v_mfma_i32_16x16x64_i8 v[92:95], v[60:63], v[212:215], v[92:95]
	v_mfma_i32_16x16x64_i8 v[88:91], v[68:71], v[212:215], v[88:91]
	v_mfma_i32_16x16x64_i8 v[134:137], v[156:159], v[172:175], v[134:137]
	v_mfma_i32_16x16x64_i8 v[130:133], v[164:167], v[172:175], v[130:133]
	v_mfma_i32_16x16x64_i8 v[118:121], v[156:159], v[180:183], v[118:121]
	v_mfma_i32_16x16x64_i8 v[114:117], v[164:167], v[180:183], v[114:117]
	v_mfma_i32_16x16x64_i8 v[102:105], v[156:159], v[200:203], v[102:105]
	v_mfma_i32_16x16x64_i8 v[98:101], v[164:167], v[200:203], v[98:101]
	v_mfma_i32_16x16x64_i8 v[84:87], v[156:159], v[208:211], v[84:87]
	v_mfma_i32_16x16x64_i8 v[80:83], v[164:167], v[208:211], v[80:83]
	v_mfma_i32_16x16x64_i8 v[134:137], v[160:163], v[176:179], v[134:137]
	v_mfma_i32_16x16x64_i8 v[130:133], v[168:171], v[176:179], v[130:133]
	v_mfma_i32_16x16x64_i8 v[118:121], v[160:163], v[190:193], v[118:121]
	v_mfma_i32_16x16x64_i8 v[114:117], v[168:171], v[190:193], v[114:117]
	v_mfma_i32_16x16x64_i8 v[102:105], v[160:163], v[204:207], v[102:105]
	v_mfma_i32_16x16x64_i8 v[98:101], v[168:171], v[204:207], v[98:101]
	v_mfma_i32_16x16x64_i8 v[84:87], v[160:163], v[212:215], v[84:87]
	v_mfma_i32_16x16x64_i8 v[80:83], v[168:171], v[212:215], v[80:83]
	s_barrier
; #define PG8_STAGE(bufoff, gbase, voff) do { _Pragma("unroll") for (int _i = 0; _i < 2; ++_i) \
;         __builtin_amdgcn_global_load_lds((const unsigned*)((const char*)(gbase) + (voff)[_i]), (PG8_LAS unsigned*)(lds + (bufoff) + ldsw + _i * 8192), 16, 0, 0); } while (0)
; #define PG8_LDA(dst, b, h) do { _Pragma("unroll") for (int m = 0; m < 4; ++m) _Pragma("unroll") for (int k = 0; k < 2; ++k) dst[m][k] = *(const PG8_LAS bf16x8*)(lds + PG8_SA(b, h) + aoff + m * 2048 + k * 1024); } while (0)
; #define PG8_MMA(ai, bj, At, Bt) do { __builtin_amdgcn_s_setprio(1); _Pragma("unroll") for (int m = 0; m < 4; ++m) _Pragma("unroll") for (int n = 0; n < 2; ++n) _Pragma("unroll") for (int k = 0; k < 2; ++k) \
;         mma1<I8>(acc[ai][bj][m][n], Bt[n][k], At[m][k]); __builtin_amdgcn_s_setprio(0); } while (0)
; #define PG8_WAIT_V(n) asm volatile("s_waitcnt vmcnt(" #n ")" ::: "memory")
; #define PG8_WAIT_L(n) asm volatile("s_waitcnt lgkmcnt(" #n ")" ::: "memory")
; #define PG8_BAR __builtin_amdgcn_s_barrier()
; #define PG8_SCHED __builtin_amdgcn_sched_barrier(0)
; template <class Epi, class Sched, bool ALIGN_EPI = false, bool SP2 = false, bool I8 = false>
; __device__ __forceinline__ void gemm_phase(PG8_LAS unsigned char* lds, const Gemm g, const Sched& S, const Epi& E, const int tid) {
;     ...
;             PG8_LDA(At, 1, 1); PG8_STAGE(PG8_SB(1, 0), b3, voffB); PG8_STAGE(PG8_SB(1, 1), b3 + hstepB, voffB); PG8_STAGE(PG8_SA(1, 0), a3, voffA);
;             PG8_WAIT_V(8); PG8_WAIT_L(0); PG8_BAR; PG8_MMA(1, 0, At, B0); PG8_MMA(1, 1, At, B1); PG8_BAR; PG8_SCHED;
;     ...
;         if constexpr (ALIGN_EPI) { if (wr == 0) PG8_BAR; }
	s_setprio 0
	s_add_i32 s56, s70, s75
	v_lshl_add_u64 v[184:185], v[184:185], 0, s[42:43]
	s_mov_b32 m0, s56
	ds_read_b128 v[172:175], v189 offset:49152
	ds_read_b128 v[176:179], v189 offset:50176
	ds_read_b128 v[180:183], v189 offset:51200
	ds_read_b128 v[190:193], v189 offset:52224
	ds_read_b128 v[200:203], v189 offset:53248
	ds_read_b128 v[204:207], v189 offset:54272
	ds_read_b128 v[208:211], v189 offset:55296
	ds_read_b128 v[212:215], v189 offset:56320
	global_load_lds_dwordx4 v[184:185], off
	s_add_i32 m0, s56, 0x2000
	s_add_u32 s54, s54, 0x80080
	v_lshl_add_u64 v[184:185], v[194:195], 0, s[42:43]
	s_addc_u32 s55, s55, 0
	s_add_i32 s56, s76, s75
	global_load_lds_dwordx4 v[184:185], off
	v_lshl_add_u64 v[184:185], s[54:55], 0, v[96:97]
	s_mov_b32 m0, s56
	s_nop 0
	global_load_lds_dwordx4 v[184:185], off
	v_lshl_add_u64 v[184:185], s[54:55], 0, v[150:151]
	s_add_i32 m0, s56, 0x2000
	s_nop 0
	global_load_lds_dwordx4 v[184:185], off
	v_lshl_add_u64 v[184:185], v[216:217], 0, s[42:43]
	s_mov_b32 m0, s89
	s_nop 0
	global_load_lds_dwordx4 v[184:185], off
	v_lshl_add_u64 v[184:185], v[218:219], 0, s[42:43]
	s_mov_b32 m0, s90
	s_nop 0
	global_load_lds_dwordx4 v[184:185], off
	s_waitcnt vmcnt(8)
	s_waitcnt lgkmcnt(0)
	s_setprio 1
	s_barrier
	v_mfma_i32_16x16x64_i8 v[76:79], v[56:59], v[172:175], v[76:79]
	v_mfma_i32_16x16x64_i8 v[72:75], v[64:67], v[172:175], v[72:75]
	v_mfma_i32_16x16x64_i8 v[44:47], v[56:59], v[180:183], v[44:47]
	v_mfma_i32_16x16x64_i8 v[40:43], v[64:67], v[180:183], v[40:43]
	v_mfma_i32_16x16x64_i8 v[28:31], v[56:59], v[200:203], v[28:31]
	v_mfma_i32_16x16x64_i8 v[24:27], v[64:67], v[200:203], v[24:27]
	v_mfma_i32_16x16x64_i8 v[12:15], v[56:59], v[208:211], v[12:15]
	v_mfma_i32_16x16x64_i8 v[8:11], v[64:67], v[208:211], v[8:11]
	v_mfma_i32_16x16x64_i8 v[76:79], v[60:63], v[176:179], v[76:79]
	v_mfma_i32_16x16x64_i8 v[72:75], v[68:71], v[176:179], v[72:75]
	v_mfma_i32_16x16x64_i8 v[44:47], v[60:63], v[190:193], v[44:47]
	v_mfma_i32_16x16x64_i8 v[40:43], v[68:71], v[190:193], v[40:43]
	v_mfma_i32_16x16x64_i8 v[28:31], v[60:63], v[204:207], v[28:31]
	v_mfma_i32_16x16x64_i8 v[24:27], v[68:71], v[204:207], v[24:27]
	v_mfma_i32_16x16x64_i8 v[12:15], v[60:63], v[212:215], v[12:15]
	v_mfma_i32_16x16x64_i8 v[8:11], v[68:71], v[212:215], v[8:11]
	v_mfma_i32_16x16x64_i8 v[48:51], v[156:159], v[172:175], v[48:51]
	v_mfma_i32_16x16x64_i8 v[60:63], v[160:163], v[176:179], v[48:51]
	v_mfma_i32_16x16x64_i8 v[48:51], v[164:167], v[172:175], v[52:55]
	v_mfma_i32_16x16x64_i8 v[36:39], v[156:159], v[180:183], v[36:39]
	v_mfma_i32_16x16x64_i8 v[32:35], v[164:167], v[180:183], v[32:35]
	v_mfma_i32_16x16x64_i8 v[20:23], v[156:159], v[200:203], v[20:23]
	v_mfma_i32_16x16x64_i8 v[16:19], v[164:167], v[200:203], v[16:19]
	v_mfma_i32_16x16x64_i8 v[4:7], v[156:159], v[208:211], v[4:7]
	v_mfma_i32_16x16x64_i8 v[0:3], v[164:167], v[208:211], v[0:3]
	v_mfma_i32_16x16x64_i8 v[56:59], v[168:171], v[176:179], v[48:51]
	v_mfma_i32_16x16x64_i8 v[36:39], v[160:163], v[190:193], v[36:39]
	v_mfma_i32_16x16x64_i8 v[32:35], v[168:171], v[190:193], v[32:35]
	v_mfma_i32_16x16x64_i8 v[20:23], v[160:163], v[204:207], v[20:23]
	v_mfma_i32_16x16x64_i8 v[16:19], v[168:171], v[204:207], v[16:19]
	v_mfma_i32_16x16x64_i8 v[4:7], v[160:163], v[212:215], v[4:7]
	v_mfma_i32_16x16x64_i8 v[0:3], v[168:171], v[212:215], v[0:3]
	s_barrier
	s_setprio 0
	s_add_i32 s65, s65, 2
	s_add_u32 s49, s49, 0x100
	s_addc_u32 s60, s60, 0
	s_add_u32 s46, s46, 0x100
	s_addc_u32 s47, s47, 0
	s_cmp_gt_u32 s65, 29
	s_cbranch_scc0 .LBB0_335
	s_and_b64 vcc, exec, s[26:27]
	s_cbranch_vccz .LBB0_338
	s_barrier

; #define PG8_STAGE(bufoff, gbase, voff) do { _Pragma("unroll") for (int _i = 0; _i < 2; ++_i) \
;         __builtin_amdgcn_global_load_lds((const unsigned*)((const char*)(gbase) + (voff)[_i]), (PG8_LAS unsigned*)(lds + (bufoff) + ldsw + _i * 8192), 16, 0, 0); } while (0)
; #define PG8_LDA(dst, b, h) do { _Pragma("unroll") for (int m = 0; m < 4; ++m) _Pragma("unroll") for (int k = 0; k < 2; ++k) dst[m][k] = *(const PG8_LAS bf16x8*)(lds + PG8_SA(b, h) + aoff + m * 2048 + k * 1024); } while (0)
; #define PG8_LDB(dst, b, h) do { _Pragma("unroll") for (int n = 0; n < 2; ++n) _Pragma("unroll") for (int k = 0; k < 2; ++k) dst[n][k] = *(const PG8_LAS bf16x8*)(lds + PG8_SB(b, h) + boff + n * 2048 + k * 1024); } while (0)
; #define PG8_MMA(ai, bj, At, Bt) do { __builtin_amdgcn_s_setprio(1); _Pragma("unroll") for (int m = 0; m < 4; ++m) _Pragma("unroll") for (int n = 0; n < 2; ++n) _Pragma("unroll") for (int k = 0; k < 2; ++k) \
;         mma1<I8>(acc[ai][bj][m][n], Bt[n][k], At[m][k]); __builtin_amdgcn_s_setprio(0); } while (0)
; #define PG8_WAIT_V(n) asm volatile("s_waitcnt vmcnt(" #n ")" ::: "memory")
; #define PG8_WAIT_L(n) asm volatile("s_waitcnt lgkmcnt(" #n ")" ::: "memory")
; #define PG8_BAR __builtin_amdgcn_s_barrier()
; #define PG8_SCHED __builtin_amdgcn_sched_barrier(0)
; template <class Epi, class Sched, bool ALIGN_EPI = false, bool SP2 = false, bool I8 = false>
; __device__ __forceinline__ void gemm_phase(PG8_LAS unsigned char* lds, const Gemm g, const Sched& S, const Epi& E, const int tid) {
;     ...
;         for (int t = 0; t < nt; t += 2) {
;             const bool last = (t == nt - 2);
;             const char* a1 = cA + (size_t)(t + 1) * kstep;
;             const char* a2 = last ? nA : cA + (size_t)(t + 2) * kstep; const char* b2 = last ? nB : cB + (size_t)(t + 2) * kstep;
;             const char* a3 = a2 + kstep; const char* b3 = b2 + kstep;
;             if (last && has_next) S.a_ready(nxt);
;             if constexpr (SP2) {
;             PG8_LDB(B0, 0, 0); PG8_LDB(B1, 0, 1); PG8_SCHED; PG8_LDA(At, 0, 0); PG8_STAGE(PG8_SA(1, 1), a1 + hstepA, voffA);
;             PG8_WAIT_V(8); PG8_WAIT_L(0); PG8_BAR; PG8_MMA(0, 0, At, B0); PG8_MMA(0, 1, At, B1); PG8_BAR; PG8_SCHED;
;             PG8_LDA(At, 0, 1); PG8_STAGE(PG8_SB(0, 0), b2, voffB); PG8_STAGE(PG8_SB(0, 1), b2 + hstepB, voffB); PG8_STAGE(PG8_SA(0, 0), a2, voffA);
.LBB0_707:
	s_add_u32 s16, s12, s54
	s_addc_u32 s56, s13, s55
	s_add_u32 s16, s16, 0x100
	s_addc_u32 s56, s56, 0
	s_add_u32 vcc_lo, s77, s54
	s_addc_u32 s57, s60, s55
	s_add_i32 vcc_hi, 0, 0x10000
	s_cmpk_eq_i32 s54, 0x1f00
	s_cselect_b32 s59, s11, s56
	s_cselect_b32 s58, s37, s16
	v_add_u32_e32 v96, vcc_hi, v221
	s_cselect_b32 s57, s49, s57
	s_cselect_b32 s56, s87, vcc_lo
	s_add_i32 s16, 0, 0x14000
	ds_read_b128 v[132:135], v96
	ds_read_b128 v[136:139], v96 offset:1024
	ds_read_b128 v[140:143], v96 offset:2048
	ds_read_b128 v[144:147], v96 offset:3072
	v_add_u32_e32 v96, s16, v221
	ds_read_b128 v[148:151], v96
	ds_read_b128 v[152:155], v96 offset:1024
	ds_read_b128 v[156:159], v96 offset:2048
	ds_read_b128 v[160:163], v96 offset:3072
	v_lshl_add_u64 v[98:99], v[214:215], 0, s[54:55]
	s_add_i32 m0, s66, 0xc000
	ds_read_b128 v[164:167], v224
	ds_read_b128 v[168:171], v224 offset:1024
	ds_read_b128 v[172:175], v224 offset:2048
	ds_read_b128 v[176:179], v224 offset:3072
	ds_read_b128 v[180:183], v224 offset:4096
	ds_read_b128 v[184:187], v224 offset:5120
	ds_read_b128 v[188:191], v224 offset:6144
	ds_read_b128 v[192:195], v224 offset:7168
	global_load_lds_dwordx4 v[98:99], off
	v_lshl_add_u64 v[98:99], v[212:213], 0, s[54:55]
	s_add_i32 m0, s66, 0xe000
	s_nop 0
	global_load_lds_dwordx4 v[98:99], off
	s_waitcnt vmcnt(8)
	s_waitcnt lgkmcnt(0)
	s_setprio 1
	s_barrier
	v_mfma_f32_16x16x32_bf16 v[128:131], v[132:135], v[164:167], v[128:131]
	v_mfma_f32_16x16x32_bf16 v[124:127], v[140:143], v[164:167], v[124:127]
	v_mfma_f32_16x16x32_bf16 v[112:115], v[132:135], v[172:175], v[112:115]
	v_mfma_f32_16x16x32_bf16 v[108:111], v[140:143], v[172:175], v[108:111]
	v_mfma_f32_16x16x32_bf16 v[92:95], v[132:135], v[180:183], v[92:95]
	v_mfma_f32_16x16x32_bf16 v[88:91], v[140:143], v[180:183], v[88:91]
	v_mfma_f32_16x16x32_bf16 v[76:79], v[132:135], v[188:191], v[76:79]
	v_mfma_f32_16x16x32_bf16 v[72:75], v[140:143], v[188:191], v[72:75]
	v_mfma_f32_16x16x32_bf16 v[128:131], v[136:139], v[168:171], v[128:131]
	v_mfma_f32_16x16x32_bf16 v[124:127], v[144:147], v[168:171], v[124:127]
	v_mfma_f32_16x16x32_bf16 v[112:115], v[136:139], v[176:179], v[112:115]
	v_mfma_f32_16x16x32_bf16 v[108:111], v[144:147], v[176:179], v[108:111]
	v_mfma_f32_16x16x32_bf16 v[92:95], v[136:139], v[184:187], v[92:95]
	v_mfma_f32_16x16x32_bf16 v[88:91], v[144:147], v[184:187], v[88:91]
	v_mfma_f32_16x16x32_bf16 v[76:79], v[136:139], v[192:195], v[76:79]
	v_mfma_f32_16x16x32_bf16 v[72:75], v[144:147], v[192:195], v[72:75]
	v_mfma_f32_16x16x32_bf16 v[120:123], v[148:151], v[164:167], v[120:123]
	v_mfma_f32_16x16x32_bf16 v[116:119], v[156:159], v[164:167], v[116:119]
	v_mfma_f32_16x16x32_bf16 v[104:107], v[148:151], v[172:175], v[104:107]
	v_mfma_f32_16x16x32_bf16 v[98:101], v[156:159], v[172:175], v[100:103]
	v_mfma_f32_16x16x32_bf16 v[84:87], v[148:151], v[180:183], v[84:87]
	v_mfma_f32_16x16x32_bf16 v[80:83], v[156:159], v[180:183], v[80:83]
	v_mfma_f32_16x16x32_bf16 v[68:71], v[148:151], v[188:191], v[68:71]
	v_mfma_f32_16x16x32_bf16 v[64:67], v[156:159], v[188:191], v[64:67]
	v_mfma_f32_16x16x32_bf16 v[120:123], v[152:155], v[168:171], v[120:123]
	v_mfma_f32_16x16x32_bf16 v[116:119], v[160:163], v[168:171], v[116:119]
	v_mfma_f32_16x16x32_bf16 v[104:107], v[152:155], v[176:179], v[104:107]
	v_mfma_f32_16x16x32_bf16 v[98:101], v[160:163], v[176:179], v[98:101]
	v_mfma_f32_16x16x32_bf16 v[84:87], v[152:155], v[184:187], v[84:87]
	v_mfma_f32_16x16x32_bf16 v[80:83], v[160:163], v[184:187], v[80:83]
	v_mfma_f32_16x16x32_bf16 v[68:71], v[152:155], v[192:195], v[68:71]
	v_mfma_f32_16x16x32_bf16 v[64:67], v[160:163], v[192:195], v[64:67]
	s_barrier
	s_setprio 0
	s_add_i32 vcc_lo, vcc_hi, s63
	v_lshl_add_u64 v[216:217], s[56:57], 0, v[202:203]
	s_mov_b32 m0, vcc_lo
	ds_read_b128 v[164:167], v224 offset:16384
	ds_read_b128 v[168:171], v224 offset:17408
	ds_read_b128 v[172:175], v224 offset:18432
	ds_read_b128 v[176:179], v224 offset:19456
	ds_read_b128 v[180:183], v224 offset:20480
	ds_read_b128 v[184:187], v224 offset:21504
	ds_read_b128 v[188:191], v224 offset:22528
	ds_read_b128 v[192:195], v224 offset:23552
	global_load_lds_dwordx4 v[216:217], off
	s_add_i32 m0, vcc_lo, 0x2000
	s_add_u32 vcc_lo, s56, 0x100000
	v_lshl_add_u64 v[226:227], s[56:57], 0, v[206:207]
	s_addc_u32 vcc_hi, s57, 0
	s_add_i32 s16, s16, s63
	global_load_lds_dwordx4 v[226:227], off
	v_lshl_add_u64 v[102:103], vcc, 0, v[202:203]
	s_mov_b32 m0, s16
	v_lshl_add_u64 v[228:229], s[58:59], 0, v[200:201]
	global_load_lds_dwordx4 v[102:103], off
	v_lshl_add_u64 v[102:103], vcc, 0, v[206:207]
	s_add_i32 m0, s16, 0x2000
	v_lshl_add_u64 v[230:231], s[58:59], 0, v[204:205]
	global_load_lds_dwordx4 v[102:103], off
	s_mov_b32 m0, s66
	s_nop 0
	global_load_lds_dwordx4 v[228:229], off
	s_mov_b32 m0, s74
	s_nop 0
	global_load_lds_dwordx4 v[230:231], off
	s_waitcnt vmcnt(8)
	s_waitcnt lgkmcnt(0)
	s_setprio 1
	s_barrier
; #define PG8_STAGE(bufoff, gbase, voff) do { _Pragma("unroll") for (int _i = 0; _i < 2; ++_i) \
;         __builtin_amdgcn_global_load_lds((const unsigned*)((const char*)(gbase) + (voff)[_i]), (PG8_LAS unsigned*)(lds + (bufoff) + ldsw + _i * 8192), 16, 0, 0); } while (0)
; #define PG8_LDA(dst, b, h) do { _Pragma("unroll") for (int m = 0; m < 4; ++m) _Pragma("unroll") for (int k = 0; k < 2; ++k) dst[m][k] = *(const PG8_LAS bf16x8*)(lds + PG8_SA(b, h) + aoff + m * 2048 + k * 1024); } while (0)
; #define PG8_LDB(dst, b, h) do { _Pragma("unroll") for (int n = 0; n < 2; ++n) _Pragma("unroll") for (int k = 0; k < 2; ++k) dst[n][k] = *(const PG8_LAS bf16x8*)(lds + PG8_SB(b, h) + boff + n * 2048 + k * 1024); } while (0)
; #define PG8_MMA(ai, bj, At, Bt) do { __builtin_amdgcn_s_setprio(1); _Pragma("unroll") for (int m = 0; m < 4; ++m) _Pragma("unroll") for (int n = 0; n < 2; ++n) _Pragma("unroll") for (int k = 0; k < 2; ++k) \
;         mma1<I8>(acc[ai][bj][m][n], Bt[n][k], At[m][k]); __builtin_amdgcn_s_setprio(0); } while (0)
; #define PG8_WAIT_V(n) asm volatile("s_waitcnt vmcnt(" #n ")" ::: "memory")
; #define PG8_WAIT_L(n) asm volatile("s_waitcnt lgkmcnt(" #n ")" ::: "memory")
; #define PG8_BAR __builtin_amdgcn_s_barrier()
; #define PG8_SCHED __builtin_amdgcn_sched_barrier(0)
; template <class Epi, class Sched, bool ALIGN_EPI = false, bool SP2 = false, bool I8 = false>
; __device__ __forceinline__ void gemm_phase(PG8_LAS unsigned char* lds, const Gemm g, const Sched& S, const Epi& E, const int tid) {
;     ...
;             PG8_WAIT_V(8); PG8_WAIT_L(0); PG8_BAR; PG8_MMA(1, 0, At, B0); PG8_MMA(1, 1, At, B1); PG8_BAR; PG8_SCHED;
;             PG8_LDB(B0, 1, 0); PG8_LDB(B1, 1, 1); PG8_SCHED; PG8_LDA(At, 1, 0); PG8_STAGE(PG8_SA(0, 1), a2 + hstepA, voffA);
;             PG8_WAIT_V(8); PG8_WAIT_L(0); PG8_BAR; PG8_MMA(0, 0, At, B0); PG8_MMA(0, 1, At, B1); PG8_BAR; PG8_SCHED;
	v_mfma_f32_16x16x32_bf16 v[60:63], v[132:135], v[164:167], v[60:63]
	v_mfma_f32_16x16x32_bf16 v[56:59], v[140:143], v[164:167], v[56:59]
	v_mfma_f32_16x16x32_bf16 v[44:47], v[132:135], v[172:175], v[44:47]
	v_mfma_f32_16x16x32_bf16 v[40:43], v[140:143], v[172:175], v[40:43]
	v_mfma_f32_16x16x32_bf16 v[28:31], v[132:135], v[180:183], v[28:31]
	v_mfma_f32_16x16x32_bf16 v[24:27], v[140:143], v[180:183], v[24:27]
	v_mfma_f32_16x16x32_bf16 v[12:15], v[132:135], v[188:191], v[12:15]
	v_mfma_f32_16x16x32_bf16 v[8:11], v[140:143], v[188:191], v[8:11]
	v_mfma_f32_16x16x32_bf16 v[60:63], v[136:139], v[168:171], v[60:63]
	v_mfma_f32_16x16x32_bf16 v[56:59], v[144:147], v[168:171], v[56:59]
	v_mfma_f32_16x16x32_bf16 v[44:47], v[136:139], v[176:179], v[44:47]
	v_mfma_f32_16x16x32_bf16 v[40:43], v[144:147], v[176:179], v[40:43]
	v_mfma_f32_16x16x32_bf16 v[28:31], v[136:139], v[184:187], v[28:31]
	v_mfma_f32_16x16x32_bf16 v[24:27], v[144:147], v[184:187], v[24:27]
	v_mfma_f32_16x16x32_bf16 v[12:15], v[136:139], v[192:195], v[12:15]
	v_mfma_f32_16x16x32_bf16 v[8:11], v[144:147], v[192:195], v[8:11]
	v_mfma_f32_16x16x32_bf16 v[52:55], v[148:151], v[164:167], v[52:55]
	v_mfma_f32_16x16x32_bf16 v[48:51], v[156:159], v[164:167], v[48:51]
	v_mfma_f32_16x16x32_bf16 v[36:39], v[148:151], v[172:175], v[36:39]
	v_mfma_f32_16x16x32_bf16 v[32:35], v[156:159], v[172:175], v[32:35]
	v_mfma_f32_16x16x32_bf16 v[20:23], v[148:151], v[180:183], v[20:23]
	v_mfma_f32_16x16x32_bf16 v[16:19], v[156:159], v[180:183], v[16:19]
	v_mfma_f32_16x16x32_bf16 v[4:7], v[148:151], v[188:191], v[4:7]
	v_mfma_f32_16x16x32_bf16 v[0:3], v[156:159], v[188:191], v[0:3]
	v_mfma_f32_16x16x32_bf16 v[52:55], v[152:155], v[168:171], v[52:55]
	v_mfma_f32_16x16x32_bf16 v[48:51], v[160:163], v[168:171], v[48:51]
	v_mfma_f32_16x16x32_bf16 v[36:39], v[152:155], v[176:179], v[36:39]
	v_mfma_f32_16x16x32_bf16 v[32:35], v[160:163], v[176:179], v[32:35]
	v_mfma_f32_16x16x32_bf16 v[20:23], v[152:155], v[184:187], v[20:23]
	v_mfma_f32_16x16x32_bf16 v[16:19], v[160:163], v[184:187], v[16:19]
	v_mfma_f32_16x16x32_bf16 v[4:7], v[152:155], v[192:195], v[4:7]
	v_mfma_f32_16x16x32_bf16 v[0:3], v[160:163], v[192:195], v[0:3]
	s_barrier
	s_setprio 0
	s_add_i32 s16, 0, 0x18000
	v_add_u32_e32 v96, s16, v221
	s_add_i32 vcc_lo, 0, 0x1c000
	ds_read_b128 v[132:135], v96
	ds_read_b128 v[136:139], v96 offset:1024
	ds_read_b128 v[140:143], v96 offset:2048
	ds_read_b128 v[144:147], v96 offset:3072
	v_add_u32_e32 v96, vcc_lo, v221
	ds_read_b128 v[148:151], v96
	ds_read_b128 v[152:155], v96 offset:1024
	ds_read_b128 v[156:159], v96 offset:2048
	ds_read_b128 v[160:163], v96 offset:3072
	s_add_u32 s58, s58, 0x100000
	s_addc_u32 s59, s59, 0
	s_mov_b32 m0, s75
	v_lshl_add_u64 v[102:103], s[58:59], 0, v[200:201]
	ds_read_b128 v[164:167], v224 offset:32768
	ds_read_b128 v[168:171], v224 offset:33792
	ds_read_b128 v[172:175], v224 offset:34816
	ds_read_b128 v[176:179], v224 offset:35840
	ds_read_b128 v[180:183], v224 offset:36864
	ds_read_b128 v[184:187], v224 offset:37888
	ds_read_b128 v[188:191], v224 offset:38912
	ds_read_b128 v[192:195], v224 offset:39936
	global_load_lds_dwordx4 v[102:103], off
	v_lshl_add_u64 v[102:103], s[58:59], 0, v[204:205]
	s_mov_b32 m0, s80
	s_nop 0
	global_load_lds_dwordx4 v[102:103], off
	s_waitcnt vmcnt(8)
	s_waitcnt lgkmcnt(0)
	s_setprio 1
	s_barrier
	v_mfma_f32_16x16x32_bf16 v[128:131], v[132:135], v[164:167], v[128:131]
	v_mfma_f32_16x16x32_bf16 v[124:127], v[140:143], v[164:167], v[124:127]
	v_mfma_f32_16x16x32_bf16 v[112:115], v[132:135], v[172:175], v[112:115]
	v_mfma_f32_16x16x32_bf16 v[108:111], v[140:143], v[172:175], v[108:111]
	v_mfma_f32_16x16x32_bf16 v[92:95], v[132:135], v[180:183], v[92:95]
	v_mfma_f32_16x16x32_bf16 v[88:91], v[140:143], v[180:183], v[88:91]
	v_mfma_f32_16x16x32_bf16 v[76:79], v[132:135], v[188:191], v[76:79]
	v_mfma_f32_16x16x32_bf16 v[72:75], v[140:143], v[188:191], v[72:75]
	v_mfma_f32_16x16x32_bf16 v[128:131], v[136:139], v[168:171], v[128:131]
	v_mfma_f32_16x16x32_bf16 v[124:127], v[144:147], v[168:171], v[124:127]
	v_mfma_f32_16x16x32_bf16 v[112:115], v[136:139], v[176:179], v[112:115]
	v_mfma_f32_16x16x32_bf16 v[108:111], v[144:147], v[176:179], v[108:111]
	v_mfma_f32_16x16x32_bf16 v[92:95], v[136:139], v[184:187], v[92:95]
	v_mfma_f32_16x16x32_bf16 v[88:91], v[144:147], v[184:187], v[88:91]
	v_mfma_f32_16x16x32_bf16 v[76:79], v[136:139], v[192:195], v[76:79]
	v_mfma_f32_16x16x32_bf16 v[72:75], v[144:147], v[192:195], v[72:75]
	v_mfma_f32_16x16x32_bf16 v[120:123], v[148:151], v[164:167], v[120:123]
	v_mfma_f32_16x16x32_bf16 v[116:119], v[156:159], v[164:167], v[116:119]
	v_mfma_f32_16x16x32_bf16 v[102:105], v[148:151], v[172:175], v[104:107]
	v_mfma_f32_16x16x32_bf16 v[98:101], v[156:159], v[172:175], v[98:101]
	v_mfma_f32_16x16x32_bf16 v[84:87], v[148:151], v[180:183], v[84:87]
	v_mfma_f32_16x16x32_bf16 v[80:83], v[156:159], v[180:183], v[80:83]
	v_mfma_f32_16x16x32_bf16 v[68:71], v[148:151], v[188:191], v[68:71]
	v_mfma_f32_16x16x32_bf16 v[64:67], v[156:159], v[188:191], v[64:67]
	v_mfma_f32_16x16x32_bf16 v[120:123], v[152:155], v[168:171], v[120:123]
	v_mfma_f32_16x16x32_bf16 v[116:119], v[160:163], v[168:171], v[116:119]
	v_mfma_f32_16x16x32_bf16 v[104:107], v[152:155], v[176:179], v[102:105]
	v_mfma_f32_16x16x32_bf16 v[100:103], v[160:163], v[176:179], v[98:101]
	v_mfma_f32_16x16x32_bf16 v[84:87], v[152:155], v[184:187], v[84:87]
	v_mfma_f32_16x16x32_bf16 v[80:83], v[160:163], v[184:187], v[80:83]
	v_mfma_f32_16x16x32_bf16 v[68:71], v[152:155], v[192:195], v[68:71]
	v_mfma_f32_16x16x32_bf16 v[64:67], v[160:163], v[192:195], v[64:67]
	s_barrier
; #define PG8_STAGE(bufoff, gbase, voff) do { _Pragma("unroll") for (int _i = 0; _i < 2; ++_i) \
;         __builtin_amdgcn_global_load_lds((const unsigned*)((const char*)(gbase) + (voff)[_i]), (PG8_LAS unsigned*)(lds + (bufoff) + ldsw + _i * 8192), 16, 0, 0); } while (0)
; #define PG8_LDA(dst, b, h) do { _Pragma("unroll") for (int m = 0; m < 4; ++m) _Pragma("unroll") for (int k = 0; k < 2; ++k) dst[m][k] = *(const PG8_LAS bf16x8*)(lds + PG8_SA(b, h) + aoff + m * 2048 + k * 1024); } while (0)
; #define PG8_MMA(ai, bj, At, Bt) do { __builtin_amdgcn_s_setprio(1); _Pragma("unroll") for (int m = 0; m < 4; ++m) _Pragma("unroll") for (int n = 0; n < 2; ++n) _Pragma("unroll") for (int k = 0; k < 2; ++k) \
;         mma1<I8>(acc[ai][bj][m][n], Bt[n][k], At[m][k]); __builtin_amdgcn_s_setprio(0); } while (0)
; #define PG8_WAIT_V(n) asm volatile("s_waitcnt vmcnt(" #n ")" ::: "memory")
; #define PG8_WAIT_L(n) asm volatile("s_waitcnt lgkmcnt(" #n ")" ::: "memory")
; #define PG8_BAR __builtin_amdgcn_s_barrier()
; #define PG8_SCHED __builtin_amdgcn_sched_barrier(0)
; template <class Epi, class Sched, bool ALIGN_EPI = false, bool SP2 = false, bool I8 = false>
; __device__ __forceinline__ void gemm_phase(PG8_LAS unsigned char* lds, const Gemm g, const Sched& S, const Epi& E, const int tid) {
;     ...
;             PG8_LDA(At, 1, 1); PG8_STAGE(PG8_SB(1, 0), b3, voffB); PG8_STAGE(PG8_SB(1, 1), b3 + hstepB, voffB); PG8_STAGE(PG8_SA(1, 0), a3, voffA);
;             PG8_WAIT_V(8); PG8_WAIT_L(0); PG8_BAR; PG8_MMA(1, 0, At, B0); PG8_MMA(1, 1, At, B1); PG8_BAR; PG8_SCHED;
;             if constexpr (HasMid<Epi>::value) { if (t + 2 == Epi::SEAM0 || t + 2 == Epi::SEAM1) E.mid(acc, cur, t + 2 == Epi::SEAM0 ? 0 : 1, wr, wc, fr, fq); }
	s_setprio 0
	s_add_i32 s16, s16, s63
	v_lshl_add_u64 v[98:99], v[216:217], 0, s[42:43]
	s_mov_b32 m0, s16
	ds_read_b128 v[164:167], v224 offset:49152
	ds_read_b128 v[168:171], v224 offset:50176
	ds_read_b128 v[172:175], v224 offset:51200
	ds_read_b128 v[176:179], v224 offset:52224
	ds_read_b128 v[180:183], v224 offset:53248
	ds_read_b128 v[184:187], v224 offset:54272
	ds_read_b128 v[188:191], v224 offset:55296
	ds_read_b128 v[192:195], v224 offset:56320
	global_load_lds_dwordx4 v[98:99], off
	s_add_i32 m0, s16, 0x2000
	s_add_u32 s56, s56, 0x100080
	v_lshl_add_u64 v[98:99], v[226:227], 0, s[42:43]
	s_addc_u32 s57, s57, 0
	s_add_i32 s16, vcc_lo, s63
	global_load_lds_dwordx4 v[98:99], off
	v_lshl_add_u64 v[98:99], s[56:57], 0, v[202:203]
	s_mov_b32 m0, s16
	s_nop 0
	global_load_lds_dwordx4 v[98:99], off
	v_lshl_add_u64 v[98:99], s[56:57], 0, v[206:207]
	s_add_i32 m0, s16, 0x2000
	s_nop 0
	global_load_lds_dwordx4 v[98:99], off
	v_lshl_add_u64 v[98:99], v[228:229], 0, s[42:43]
	s_mov_b32 m0, s95
	s_nop 0
	global_load_lds_dwordx4 v[98:99], off
	v_lshl_add_u64 v[98:99], v[230:231], 0, s[42:43]
	s_mov_b32 m0, s96
	s_nop 0
	global_load_lds_dwordx4 v[98:99], off
	s_waitcnt vmcnt(8)
	s_waitcnt lgkmcnt(0)
	s_setprio 1
	s_barrier
	v_mfma_f32_16x16x32_bf16 v[60:63], v[132:135], v[164:167], v[60:63]
	v_mfma_f32_16x16x32_bf16 v[56:59], v[140:143], v[164:167], v[56:59]
	v_mfma_f32_16x16x32_bf16 v[44:47], v[132:135], v[172:175], v[44:47]
	v_mfma_f32_16x16x32_bf16 v[40:43], v[140:143], v[172:175], v[40:43]
	v_mfma_f32_16x16x32_bf16 v[28:31], v[132:135], v[180:183], v[28:31]
	v_mfma_f32_16x16x32_bf16 v[24:27], v[140:143], v[180:183], v[24:27]
	v_mfma_f32_16x16x32_bf16 v[12:15], v[132:135], v[188:191], v[12:15]
	v_mfma_f32_16x16x32_bf16 v[8:11], v[140:143], v[188:191], v[8:11]
	v_mfma_f32_16x16x32_bf16 v[60:63], v[136:139], v[168:171], v[60:63]
	v_mfma_f32_16x16x32_bf16 v[56:59], v[144:147], v[168:171], v[56:59]
	v_mfma_f32_16x16x32_bf16 v[44:47], v[136:139], v[176:179], v[44:47]
	v_mfma_f32_16x16x32_bf16 v[40:43], v[144:147], v[176:179], v[40:43]
	v_mfma_f32_16x16x32_bf16 v[28:31], v[136:139], v[184:187], v[28:31]
	v_mfma_f32_16x16x32_bf16 v[24:27], v[144:147], v[184:187], v[24:27]
	v_mfma_f32_16x16x32_bf16 v[12:15], v[136:139], v[192:195], v[12:15]
	v_mfma_f32_16x16x32_bf16 v[8:11], v[144:147], v[192:195], v[8:11]
	v_mfma_f32_16x16x32_bf16 v[52:55], v[148:151], v[164:167], v[52:55]
	v_mfma_f32_16x16x32_bf16 v[48:51], v[156:159], v[164:167], v[48:51]
	v_mfma_f32_16x16x32_bf16 v[36:39], v[148:151], v[172:175], v[36:39]
	v_mfma_f32_16x16x32_bf16 v[32:35], v[156:159], v[172:175], v[32:35]
	v_mfma_f32_16x16x32_bf16 v[20:23], v[148:151], v[180:183], v[20:23]
	v_mfma_f32_16x16x32_bf16 v[16:19], v[156:159], v[180:183], v[16:19]
	v_mfma_f32_16x16x32_bf16 v[4:7], v[148:151], v[188:191], v[4:7]
	v_mfma_f32_16x16x32_bf16 v[0:3], v[156:159], v[188:191], v[0:3]
	v_mfma_f32_16x16x32_bf16 v[52:55], v[152:155], v[168:171], v[52:55]
	v_mfma_f32_16x16x32_bf16 v[48:51], v[160:163], v[168:171], v[48:51]
	v_mfma_f32_16x16x32_bf16 v[36:39], v[152:155], v[176:179], v[36:39]
	v_mfma_f32_16x16x32_bf16 v[32:35], v[160:163], v[176:179], v[32:35]
	v_mfma_f32_16x16x32_bf16 v[20:23], v[152:155], v[184:187], v[20:23]
	v_mfma_f32_16x16x32_bf16 v[16:19], v[160:163], v[184:187], v[16:19]
	v_mfma_f32_16x16x32_bf16 v[4:7], v[152:155], v[192:195], v[4:7]
	v_mfma_f32_16x16x32_bf16 v[0:3], v[160:163], v[192:195], v[0:3]
	s_barrier
	s_setprio 0
	s_cmp_lt_i32 s70, 46
	s_cbranch_scc1 .LBB0_709
	s_cmp_eq_u32 s70, 46
	s_cselect_b64 s[56:57], -1, 0
	s_cbranch_execz .LBB0_710
	s_branch .LBB0_711

; #define PG8_STAGE(bufoff, gbase, voff) do { _Pragma("unroll") for (int _i = 0; _i < 2; ++_i) \
;         __builtin_amdgcn_global_load_lds((const unsigned*)((const char*)(gbase) + (voff)[_i]), (PG8_LAS unsigned*)(lds + (bufoff) + ldsw + _i * 8192), 16, 0, 0); } while (0)
; #define PG8_LDA(dst, b, h) do { _Pragma("unroll") for (int m = 0; m < 4; ++m) _Pragma("unroll") for (int k = 0; k < 2; ++k) dst[m][k] = *(const PG8_LAS bf16x8*)(lds + PG8_SA(b, h) + aoff + m * 2048 + k * 1024); } while (0)
; #define PG8_LDB(dst, b, h) do { _Pragma("unroll") for (int n = 0; n < 2; ++n) _Pragma("unroll") for (int k = 0; k < 2; ++k) dst[n][k] = *(const PG8_LAS bf16x8*)(lds + PG8_SB(b, h) + boff + n * 2048 + k * 1024); } while (0)
; #define PG8_MMA(ai, bj, At, Bt) do { __builtin_amdgcn_s_setprio(1); _Pragma("unroll") for (int m = 0; m < 4; ++m) _Pragma("unroll") for (int n = 0; n < 2; ++n) _Pragma("unroll") for (int k = 0; k < 2; ++k) \
;         mma1<I8>(acc[ai][bj][m][n], Bt[n][k], At[m][k]); __builtin_amdgcn_s_setprio(0); } while (0)
; #define PG8_WAIT_V(n) asm volatile("s_waitcnt vmcnt(" #n ")" ::: "memory")
; #define PG8_WAIT_L(n) asm volatile("s_waitcnt lgkmcnt(" #n ")" ::: "memory")
; #define PG8_BAR __builtin_amdgcn_s_barrier()
; #define PG8_SCHED __builtin_amdgcn_sched_barrier(0)
; template <class Epi, class Sched, bool ALIGN_EPI = false, bool SP2 = false, bool I8 = false>
; __device__ __forceinline__ void gemm_phase(PG8_LAS unsigned char* lds, const Gemm g, const Sched& S, const Epi& E, const int tid) {
;     ...
;         for (int t = 0; t < nt; t += 2) {
;             const bool last = (t == nt - 2);
;             const char* a1 = cA + (size_t)(t + 1) * kstep;
;             const char* a2 = last ? nA : cA + (size_t)(t + 2) * kstep; const char* b2 = last ? nB : cB + (size_t)(t + 2) * kstep;
;             const char* a3 = a2 + kstep; const char* b3 = b2 + kstep;
;             if (last && has_next) S.a_ready(nxt);
;             if constexpr (SP2) {
;             PG8_LDB(B0, 0, 0); PG8_LDB(B1, 0, 1); PG8_SCHED; PG8_LDA(At, 0, 0); PG8_STAGE(PG8_SA(1, 1), a1 + hstepA, voffA);
;             PG8_WAIT_V(8); PG8_WAIT_L(0); PG8_BAR; PG8_MMA(0, 0, At, B0); PG8_MMA(0, 1, At, B1); PG8_BAR; PG8_SCHED;
;             PG8_LDA(At, 0, 1); PG8_STAGE(PG8_SB(0, 0), b2, voffB); PG8_STAGE(PG8_SB(0, 1), b2 + hstepB, voffB); PG8_STAGE(PG8_SA(0, 0), a2, voffA);
.LBB0_940:
	s_add_u32 s12, s8, 0xfff80080
	s_addc_u32 s13, s9, -1
	s_add_i32 s59, 0, 0x10000
	s_cmp_eq_u32 s58, 28
	s_cselect_b32 s55, s7, s13
	s_cselect_b32 s54, s35, s12
	v_add_u32_e32 v96, s59, v225
	s_cselect_b32 s13, s37, s57
	s_cselect_b32 s12, s49, s56
	s_add_i32 s60, 0, 0x14000
	ds_read_b128 v[130:133], v96
	ds_read_b128 v[134:137], v96 offset:1024
	ds_read_b128 v[138:141], v96 offset:2048
	ds_read_b128 v[142:145], v96 offset:3072
	v_add_u32_e32 v96, s60, v225
	ds_read_b128 v[146:149], v96
	ds_read_b128 v[150:153], v96 offset:1024
	ds_read_b128 v[166:169], v96 offset:2048
	ds_read_b128 v[170:173], v96 offset:3072
	v_lshl_add_u64 v[194:195], s[8:9], 0, v[164:165]
	s_add_i32 m0, s3, 0xc000
	ds_read_b128 v[174:177], v226
	ds_read_b128 v[178:181], v226 offset:1024
	ds_read_b128 v[182:185], v226 offset:2048
	ds_read_b128 v[186:189], v226 offset:3072
	ds_read_b128 v[190:193], v226 offset:4096
	ds_read_b128 v[200:203], v226 offset:5120
	ds_read_b128 v[204:207], v226 offset:6144
	ds_read_b128 v[228:231], v226 offset:7168
	global_load_lds_dwordx4 v[194:195], off
	v_lshl_add_u64 v[194:195], s[8:9], 0, v[162:163]
	s_add_i32 m0, s3, 0xe000
	s_nop 0
	global_load_lds_dwordx4 v[194:195], off
	s_waitcnt vmcnt(8)
	s_waitcnt lgkmcnt(0)
	s_setprio 1
	s_barrier
	v_mfma_i32_16x16x64_i8 v[126:129], v[130:133], v[174:177], v[126:129]
	v_mfma_i32_16x16x64_i8 v[122:125], v[138:141], v[174:177], v[122:125]
	v_mfma_i32_16x16x64_i8 v[110:113], v[130:133], v[182:185], v[110:113]
	v_mfma_i32_16x16x64_i8 v[106:109], v[138:141], v[182:185], v[106:109]
	v_mfma_i32_16x16x64_i8 v[92:95], v[130:133], v[190:193], v[92:95]
	v_mfma_i32_16x16x64_i8 v[88:91], v[138:141], v[190:193], v[88:91]
	v_mfma_i32_16x16x64_i8 v[76:79], v[130:133], v[204:207], v[76:79]
	v_mfma_i32_16x16x64_i8 v[72:75], v[138:141], v[204:207], v[72:75]
	v_mfma_i32_16x16x64_i8 v[126:129], v[134:137], v[178:181], v[126:129]
	v_mfma_i32_16x16x64_i8 v[122:125], v[142:145], v[178:181], v[122:125]
	v_mfma_i32_16x16x64_i8 v[110:113], v[134:137], v[186:189], v[110:113]
	v_mfma_i32_16x16x64_i8 v[106:109], v[142:145], v[186:189], v[106:109]
	v_mfma_i32_16x16x64_i8 v[92:95], v[134:137], v[200:203], v[92:95]
	v_mfma_i32_16x16x64_i8 v[88:91], v[142:145], v[200:203], v[88:91]
	v_mfma_i32_16x16x64_i8 v[76:79], v[134:137], v[228:231], v[76:79]
	v_mfma_i32_16x16x64_i8 v[72:75], v[142:145], v[228:231], v[72:75]
	v_mfma_i32_16x16x64_i8 v[118:121], v[146:149], v[174:177], v[118:121]
	v_mfma_i32_16x16x64_i8 v[114:117], v[166:169], v[174:177], v[114:117]
	v_mfma_i32_16x16x64_i8 v[102:105], v[146:149], v[182:185], v[102:105]
	v_mfma_i32_16x16x64_i8 v[98:101], v[166:169], v[182:185], v[98:101]
	v_mfma_i32_16x16x64_i8 v[84:87], v[146:149], v[190:193], v[84:87]
	v_mfma_i32_16x16x64_i8 v[80:83], v[166:169], v[190:193], v[80:83]
	v_mfma_i32_16x16x64_i8 v[68:71], v[146:149], v[204:207], v[68:71]
	v_mfma_i32_16x16x64_i8 v[64:67], v[166:169], v[204:207], v[64:67]
	v_mfma_i32_16x16x64_i8 v[118:121], v[150:153], v[178:181], v[118:121]
	v_mfma_i32_16x16x64_i8 v[114:117], v[170:173], v[178:181], v[114:117]
	v_mfma_i32_16x16x64_i8 v[102:105], v[150:153], v[186:189], v[102:105]
	v_mfma_i32_16x16x64_i8 v[98:101], v[170:173], v[186:189], v[98:101]
	v_mfma_i32_16x16x64_i8 v[84:87], v[150:153], v[200:203], v[84:87]
	v_mfma_i32_16x16x64_i8 v[80:83], v[170:173], v[200:203], v[80:83]
	v_mfma_i32_16x16x64_i8 v[68:71], v[150:153], v[228:231], v[68:71]
	v_mfma_i32_16x16x64_i8 v[64:67], v[170:173], v[228:231], v[64:67]
	s_barrier
	s_setprio 0
	s_add_i32 s59, s59, s1
	v_lshl_add_u64 v[194:195], s[12:13], 0, v[156:157]
	s_mov_b32 m0, s59
	ds_read_b128 v[174:177], v226 offset:16384
	ds_read_b128 v[178:181], v226 offset:17408
	ds_read_b128 v[182:185], v226 offset:18432
	ds_read_b128 v[186:189], v226 offset:19456
	ds_read_b128 v[190:193], v226 offset:20480
	ds_read_b128 v[200:203], v226 offset:21504
	ds_read_b128 v[204:207], v226 offset:22528
	ds_read_b128 v[228:231], v226 offset:23552
	global_load_lds_dwordx4 v[194:195], off
	s_add_i32 m0, s59, 0x2000
	s_add_u32 s76, s12, 0x80000
	v_lshl_add_u64 v[208:209], s[12:13], 0, v[160:161]
	s_addc_u32 s77, s13, 0
	s_add_i32 s59, s60, s1
	global_load_lds_dwordx4 v[208:209], off
	v_lshl_add_u64 v[212:213], s[76:77], 0, v[156:157]
	s_mov_b32 m0, s59
	v_lshl_add_u64 v[216:217], s[54:55], 0, v[158:159]
	global_load_lds_dwordx4 v[212:213], off
	v_lshl_add_u64 v[212:213], s[76:77], 0, v[160:161]
	s_add_i32 m0, s59, 0x2000
	s_nop 0
	global_load_lds_dwordx4 v[212:213], off
	v_lshl_add_u64 v[212:213], s[54:55], 0, v[154:155]
	s_mov_b32 m0, s3
	s_nop 0
	global_load_lds_dwordx4 v[212:213], off
	s_mov_b32 m0, s19
	s_nop 0
	global_load_lds_dwordx4 v[216:217], off
	s_waitcnt vmcnt(8)
	s_waitcnt lgkmcnt(0)
	s_setprio 1
	s_barrier
; #define PG8_STAGE(bufoff, gbase, voff) do { _Pragma("unroll") for (int _i = 0; _i < 2; ++_i) \
;         __builtin_amdgcn_global_load_lds((const unsigned*)((const char*)(gbase) + (voff)[_i]), (PG8_LAS unsigned*)(lds + (bufoff) + ldsw + _i * 8192), 16, 0, 0); } while (0)
; #define PG8_LDA(dst, b, h) do { _Pragma("unroll") for (int m = 0; m < 4; ++m) _Pragma("unroll") for (int k = 0; k < 2; ++k) dst[m][k] = *(const PG8_LAS bf16x8*)(lds + PG8_SA(b, h) + aoff + m * 2048 + k * 1024); } while (0)
; #define PG8_LDB(dst, b, h) do { _Pragma("unroll") for (int n = 0; n < 2; ++n) _Pragma("unroll") for (int k = 0; k < 2; ++k) dst[n][k] = *(const PG8_LAS bf16x8*)(lds + PG8_SB(b, h) + boff + n * 2048 + k * 1024); } while (0)
; #define PG8_MMA(ai, bj, At, Bt) do { __builtin_amdgcn_s_setprio(1); _Pragma("unroll") for (int m = 0; m < 4; ++m) _Pragma("unroll") for (int n = 0; n < 2; ++n) _Pragma("unroll") for (int k = 0; k < 2; ++k) \
;         mma1<I8>(acc[ai][bj][m][n], Bt[n][k], At[m][k]); __builtin_amdgcn_s_setprio(0); } while (0)
; #define PG8_WAIT_V(n) asm volatile("s_waitcnt vmcnt(" #n ")" ::: "memory")
; #define PG8_WAIT_L(n) asm volatile("s_waitcnt lgkmcnt(" #n ")" ::: "memory")
; #define PG8_BAR __builtin_amdgcn_s_barrier()
; #define PG8_SCHED __builtin_amdgcn_sched_barrier(0)
; template <class Epi, class Sched, bool ALIGN_EPI = false, bool SP2 = false, bool I8 = false>
; __device__ __forceinline__ void gemm_phase(PG8_LAS unsigned char* lds, const Gemm g, const Sched& S, const Epi& E, const int tid) {
;     ...
;             PG8_WAIT_V(8); PG8_WAIT_L(0); PG8_BAR; PG8_MMA(1, 0, At, B0); PG8_MMA(1, 1, At, B1); PG8_BAR; PG8_SCHED;
;             PG8_LDB(B0, 1, 0); PG8_LDB(B1, 1, 1); PG8_SCHED; PG8_LDA(At, 1, 0); PG8_STAGE(PG8_SA(0, 1), a2 + hstepA, voffA);
;             PG8_WAIT_V(8); PG8_WAIT_L(0); PG8_BAR; PG8_MMA(0, 0, At, B0); PG8_MMA(0, 1, At, B1); PG8_BAR; PG8_SCHED;
	v_mfma_i32_16x16x64_i8 v[60:63], v[130:133], v[174:177], v[60:63]
	v_mfma_i32_16x16x64_i8 v[56:59], v[138:141], v[174:177], v[56:59]
	v_mfma_i32_16x16x64_i8 v[44:47], v[130:133], v[182:185], v[44:47]
	v_mfma_i32_16x16x64_i8 v[40:43], v[138:141], v[182:185], v[40:43]
	v_mfma_i32_16x16x64_i8 v[28:31], v[130:133], v[190:193], v[28:31]
	v_mfma_i32_16x16x64_i8 v[24:27], v[138:141], v[190:193], v[24:27]
	v_mfma_i32_16x16x64_i8 v[12:15], v[130:133], v[204:207], v[12:15]
	v_mfma_i32_16x16x64_i8 v[8:11], v[138:141], v[204:207], v[8:11]
	v_mfma_i32_16x16x64_i8 v[60:63], v[134:137], v[178:181], v[60:63]
	v_mfma_i32_16x16x64_i8 v[56:59], v[142:145], v[178:181], v[56:59]
	v_mfma_i32_16x16x64_i8 v[44:47], v[134:137], v[186:189], v[44:47]
	v_mfma_i32_16x16x64_i8 v[40:43], v[142:145], v[186:189], v[40:43]
	v_mfma_i32_16x16x64_i8 v[28:31], v[134:137], v[200:203], v[28:31]
	v_mfma_i32_16x16x64_i8 v[24:27], v[142:145], v[200:203], v[24:27]
	v_mfma_i32_16x16x64_i8 v[12:15], v[134:137], v[228:231], v[12:15]
	v_mfma_i32_16x16x64_i8 v[8:11], v[142:145], v[228:231], v[8:11]
	v_mfma_i32_16x16x64_i8 v[52:55], v[146:149], v[174:177], v[52:55]
	v_mfma_i32_16x16x64_i8 v[48:51], v[166:169], v[174:177], v[48:51]
	v_mfma_i32_16x16x64_i8 v[36:39], v[146:149], v[182:185], v[36:39]
	v_mfma_i32_16x16x64_i8 v[32:35], v[166:169], v[182:185], v[32:35]
	v_mfma_i32_16x16x64_i8 v[20:23], v[146:149], v[190:193], v[20:23]
	v_mfma_i32_16x16x64_i8 v[16:19], v[166:169], v[190:193], v[16:19]
	v_mfma_i32_16x16x64_i8 v[4:7], v[146:149], v[204:207], v[4:7]
	v_mfma_i32_16x16x64_i8 v[0:3], v[166:169], v[204:207], v[0:3]
	v_mfma_i32_16x16x64_i8 v[52:55], v[150:153], v[178:181], v[52:55]
	v_mfma_i32_16x16x64_i8 v[48:51], v[170:173], v[178:181], v[48:51]
	v_mfma_i32_16x16x64_i8 v[36:39], v[150:153], v[186:189], v[36:39]
	v_mfma_i32_16x16x64_i8 v[32:35], v[170:173], v[186:189], v[32:35]
	v_mfma_i32_16x16x64_i8 v[20:23], v[150:153], v[200:203], v[20:23]
	v_mfma_i32_16x16x64_i8 v[16:19], v[170:173], v[200:203], v[16:19]
	v_mfma_i32_16x16x64_i8 v[4:7], v[150:153], v[228:231], v[4:7]
	v_mfma_i32_16x16x64_i8 v[0:3], v[170:173], v[228:231], v[0:3]
	s_barrier
	s_setprio 0
	s_add_i32 s59, 0, 0x18000
	v_add_u32_e32 v96, s59, v225
	s_add_i32 s60, 0, 0x1c000
	ds_read_b128 v[130:133], v96
	ds_read_b128 v[134:137], v96 offset:1024
	ds_read_b128 v[138:141], v96 offset:2048
	ds_read_b128 v[142:145], v96 offset:3072
	v_add_u32_e32 v96, s60, v225
	ds_read_b128 v[146:149], v96
	ds_read_b128 v[150:153], v96 offset:1024
	ds_read_b128 v[166:169], v96 offset:2048
	ds_read_b128 v[170:173], v96 offset:3072
	s_add_u32 s54, s54, 0x80000
	s_addc_u32 s55, s55, 0
	s_mov_b32 m0, s48
	v_lshl_add_u64 v[232:233], s[54:55], 0, v[154:155]
	ds_read_b128 v[174:177], v226 offset:32768
	ds_read_b128 v[178:181], v226 offset:33792
	ds_read_b128 v[182:185], v226 offset:34816
	ds_read_b128 v[186:189], v226 offset:35840
	ds_read_b128 v[190:193], v226 offset:36864
	ds_read_b128 v[200:203], v226 offset:37888
	ds_read_b128 v[204:207], v226 offset:38912
	ds_read_b128 v[228:231], v226 offset:39936
	global_load_lds_dwordx4 v[232:233], off
	v_lshl_add_u64 v[232:233], s[54:55], 0, v[158:159]
	s_mov_b32 m0, s51
	s_nop 0
	global_load_lds_dwordx4 v[232:233], off
	s_waitcnt vmcnt(8)
	s_waitcnt lgkmcnt(0)
	s_setprio 1
	s_barrier
	v_mfma_i32_16x16x64_i8 v[126:129], v[130:133], v[174:177], v[126:129]
	v_mfma_i32_16x16x64_i8 v[122:125], v[138:141], v[174:177], v[122:125]
	v_mfma_i32_16x16x64_i8 v[110:113], v[130:133], v[182:185], v[110:113]
	v_mfma_i32_16x16x64_i8 v[106:109], v[138:141], v[182:185], v[106:109]
	v_mfma_i32_16x16x64_i8 v[92:95], v[130:133], v[190:193], v[92:95]
	v_mfma_i32_16x16x64_i8 v[88:91], v[138:141], v[190:193], v[88:91]
	v_mfma_i32_16x16x64_i8 v[76:79], v[130:133], v[204:207], v[76:79]
	v_mfma_i32_16x16x64_i8 v[72:75], v[138:141], v[204:207], v[72:75]
	v_mfma_i32_16x16x64_i8 v[126:129], v[134:137], v[178:181], v[126:129]
	v_mfma_i32_16x16x64_i8 v[122:125], v[142:145], v[178:181], v[122:125]
	v_mfma_i32_16x16x64_i8 v[110:113], v[134:137], v[186:189], v[110:113]
	v_mfma_i32_16x16x64_i8 v[106:109], v[142:145], v[186:189], v[106:109]
	v_mfma_i32_16x16x64_i8 v[92:95], v[134:137], v[200:203], v[92:95]
	v_mfma_i32_16x16x64_i8 v[88:91], v[142:145], v[200:203], v[88:91]
	v_mfma_i32_16x16x64_i8 v[76:79], v[134:137], v[228:231], v[76:79]
	v_mfma_i32_16x16x64_i8 v[72:75], v[142:145], v[228:231], v[72:75]
	v_mfma_i32_16x16x64_i8 v[118:121], v[146:149], v[174:177], v[118:121]
	v_mfma_i32_16x16x64_i8 v[114:117], v[166:169], v[174:177], v[114:117]
	v_mfma_i32_16x16x64_i8 v[102:105], v[146:149], v[182:185], v[102:105]
	v_mfma_i32_16x16x64_i8 v[98:101], v[166:169], v[182:185], v[98:101]
	v_mfma_i32_16x16x64_i8 v[84:87], v[146:149], v[190:193], v[84:87]
	v_mfma_i32_16x16x64_i8 v[80:83], v[166:169], v[190:193], v[80:83]
	v_mfma_i32_16x16x64_i8 v[68:71], v[146:149], v[204:207], v[68:71]
	v_mfma_i32_16x16x64_i8 v[64:67], v[166:169], v[204:207], v[64:67]
	v_mfma_i32_16x16x64_i8 v[118:121], v[150:153], v[178:181], v[118:121]
	v_mfma_i32_16x16x64_i8 v[114:117], v[170:173], v[178:181], v[114:117]
	v_mfma_i32_16x16x64_i8 v[102:105], v[150:153], v[186:189], v[102:105]
	v_mfma_i32_16x16x64_i8 v[98:101], v[170:173], v[186:189], v[98:101]
	v_mfma_i32_16x16x64_i8 v[84:87], v[150:153], v[200:203], v[84:87]
	v_mfma_i32_16x16x64_i8 v[80:83], v[170:173], v[200:203], v[80:83]
	v_mfma_i32_16x16x64_i8 v[68:71], v[150:153], v[228:231], v[68:71]
	v_mfma_i32_16x16x64_i8 v[64:67], v[170:173], v[228:231], v[64:67]
	s_barrier
; #define PG8_STAGE(bufoff, gbase, voff) do { _Pragma("unroll") for (int _i = 0; _i < 2; ++_i) \
;         __builtin_amdgcn_global_load_lds((const unsigned*)((const char*)(gbase) + (voff)[_i]), (PG8_LAS unsigned*)(lds + (bufoff) + ldsw + _i * 8192), 16, 0, 0); } while (0)
; #define PG8_LDA(dst, b, h) do { _Pragma("unroll") for (int m = 0; m < 4; ++m) _Pragma("unroll") for (int k = 0; k < 2; ++k) dst[m][k] = *(const PG8_LAS bf16x8*)(lds + PG8_SA(b, h) + aoff + m * 2048 + k * 1024); } while (0)
; #define PG8_MMA(ai, bj, At, Bt) do { __builtin_amdgcn_s_setprio(1); _Pragma("unroll") for (int m = 0; m < 4; ++m) _Pragma("unroll") for (int n = 0; n < 2; ++n) _Pragma("unroll") for (int k = 0; k < 2; ++k) \
;         mma1<I8>(acc[ai][bj][m][n], Bt[n][k], At[m][k]); __builtin_amdgcn_s_setprio(0); } while (0)
; #define PG8_WAIT_V(n) asm volatile("s_waitcnt vmcnt(" #n ")" ::: "memory")
; #define PG8_WAIT_L(n) asm volatile("s_waitcnt lgkmcnt(" #n ")" ::: "memory")
; #define PG8_BAR __builtin_amdgcn_s_barrier()
; #define PG8_SCHED __builtin_amdgcn_sched_barrier(0)
; template <class Epi, class Sched, bool ALIGN_EPI = false, bool SP2 = false, bool I8 = false>
; __device__ __forceinline__ void gemm_phase(PG8_LAS unsigned char* lds, const Gemm g, const Sched& S, const Epi& E, const int tid) {
;     ...
;             PG8_LDA(At, 1, 1); PG8_STAGE(PG8_SB(1, 0), b3, voffB); PG8_STAGE(PG8_SB(1, 1), b3 + hstepB, voffB); PG8_STAGE(PG8_SA(1, 0), a3, voffA);
;             PG8_WAIT_V(8); PG8_WAIT_L(0); PG8_BAR; PG8_MMA(1, 0, At, B0); PG8_MMA(1, 1, At, B1); PG8_BAR; PG8_SCHED;
;     ...
;         if constexpr (ALIGN_EPI) { if (wr == 0) PG8_BAR; }
	s_setprio 0
	s_add_i32 s54, s59, s1
	v_lshl_add_u64 v[194:195], v[194:195], 0, s[42:43]
	s_mov_b32 m0, s54
	ds_read_b128 v[174:177], v226 offset:49152
	ds_read_b128 v[178:181], v226 offset:50176
	ds_read_b128 v[182:185], v226 offset:51200
	ds_read_b128 v[186:189], v226 offset:52224
	ds_read_b128 v[190:193], v226 offset:53248
	ds_read_b128 v[200:203], v226 offset:54272
	ds_read_b128 v[204:207], v226 offset:55296
	ds_read_b128 v[228:231], v226 offset:56320
	global_load_lds_dwordx4 v[194:195], off
	s_add_i32 m0, s54, 0x2000
	s_add_u32 s12, s12, 0x80080
	v_lshl_add_u64 v[194:195], v[208:209], 0, s[42:43]
	s_addc_u32 s13, s13, 0
	s_add_i32 s54, s60, s1
	global_load_lds_dwordx4 v[194:195], off
	v_lshl_add_u64 v[194:195], s[12:13], 0, v[156:157]
	s_mov_b32 m0, s54
	s_nop 0
	global_load_lds_dwordx4 v[194:195], off
	v_lshl_add_u64 v[194:195], s[12:13], 0, v[160:161]
	s_add_i32 m0, s54, 0x2000
	s_nop 0
	global_load_lds_dwordx4 v[194:195], off
	v_lshl_add_u64 v[194:195], v[212:213], 0, s[42:43]
	s_mov_b32 m0, s63
	s_nop 0
	global_load_lds_dwordx4 v[194:195], off
	v_lshl_add_u64 v[194:195], v[216:217], 0, s[42:43]
	s_mov_b32 m0, s66
	s_nop 0
	global_load_lds_dwordx4 v[194:195], off
	s_waitcnt vmcnt(8)
	s_waitcnt lgkmcnt(0)
	s_setprio 1
	s_barrier
	v_mfma_i32_16x16x64_i8 v[60:63], v[130:133], v[174:177], v[60:63]
	v_mfma_i32_16x16x64_i8 v[56:59], v[138:141], v[174:177], v[56:59]
	v_mfma_i32_16x16x64_i8 v[44:47], v[130:133], v[182:185], v[44:47]
	v_mfma_i32_16x16x64_i8 v[40:43], v[138:141], v[182:185], v[40:43]
	v_mfma_i32_16x16x64_i8 v[28:31], v[130:133], v[190:193], v[28:31]
	v_mfma_i32_16x16x64_i8 v[24:27], v[138:141], v[190:193], v[24:27]
	v_mfma_i32_16x16x64_i8 v[12:15], v[130:133], v[204:207], v[12:15]
	v_mfma_i32_16x16x64_i8 v[8:11], v[138:141], v[204:207], v[8:11]
	v_mfma_i32_16x16x64_i8 v[60:63], v[134:137], v[178:181], v[60:63]
	v_mfma_i32_16x16x64_i8 v[56:59], v[142:145], v[178:181], v[56:59]
	v_mfma_i32_16x16x64_i8 v[44:47], v[134:137], v[186:189], v[44:47]
	v_mfma_i32_16x16x64_i8 v[40:43], v[142:145], v[186:189], v[40:43]
	v_mfma_i32_16x16x64_i8 v[28:31], v[134:137], v[200:203], v[28:31]
	v_mfma_i32_16x16x64_i8 v[24:27], v[142:145], v[200:203], v[24:27]
	v_mfma_i32_16x16x64_i8 v[12:15], v[134:137], v[228:231], v[12:15]
	v_mfma_i32_16x16x64_i8 v[8:11], v[142:145], v[228:231], v[8:11]
	v_mfma_i32_16x16x64_i8 v[52:55], v[146:149], v[174:177], v[52:55]
	v_mfma_i32_16x16x64_i8 v[48:51], v[166:169], v[174:177], v[48:51]
	v_mfma_i32_16x16x64_i8 v[36:39], v[146:149], v[182:185], v[36:39]
	v_mfma_i32_16x16x64_i8 v[32:35], v[166:169], v[182:185], v[32:35]
	v_mfma_i32_16x16x64_i8 v[20:23], v[146:149], v[190:193], v[20:23]
	v_mfma_i32_16x16x64_i8 v[16:19], v[166:169], v[190:193], v[16:19]
	v_mfma_i32_16x16x64_i8 v[4:7], v[146:149], v[204:207], v[4:7]
	v_mfma_i32_16x16x64_i8 v[0:3], v[166:169], v[204:207], v[0:3]
	v_mfma_i32_16x16x64_i8 v[52:55], v[150:153], v[178:181], v[52:55]
	v_mfma_i32_16x16x64_i8 v[48:51], v[170:173], v[178:181], v[48:51]
	v_mfma_i32_16x16x64_i8 v[36:39], v[150:153], v[186:189], v[36:39]
	v_mfma_i32_16x16x64_i8 v[32:35], v[170:173], v[186:189], v[32:35]
	v_mfma_i32_16x16x64_i8 v[20:23], v[150:153], v[200:203], v[20:23]
	v_mfma_i32_16x16x64_i8 v[16:19], v[170:173], v[200:203], v[16:19]
	v_mfma_i32_16x16x64_i8 v[4:7], v[150:153], v[228:231], v[4:7]
	v_mfma_i32_16x16x64_i8 v[0:3], v[170:173], v[228:231], v[0:3]
	s_barrier
	s_setprio 0
	s_add_i32 s58, s58, 2
	s_add_u32 s56, s56, 0x100
	s_addc_u32 s57, s57, 0
	s_add_u32 s8, s8, 0x100
	s_addc_u32 s9, s9, 0
	s_cmp_gt_u32 s58, 29
	s_cbranch_scc0 .LBB0_940
	s_and_b64 vcc, exec, s[26:27]
	s_cbranch_vccz .LBB0_943
	s_barrier

; #define PG8_STAGE(bufoff, gbase, voff) do { _Pragma("unroll") for (int _i = 0; _i < 2; ++_i) \
;         __builtin_amdgcn_global_load_lds((const unsigned*)((const char*)(gbase) + (voff)[_i]), (PG8_LAS unsigned*)(lds + (bufoff) + ldsw + _i * 8192), 16, 0, 0); } while (0)
; #define PG8_LDA(dst, b, h) do { _Pragma("unroll") for (int m = 0; m < 4; ++m) _Pragma("unroll") for (int k = 0; k < 2; ++k) dst[m][k] = *(const PG8_LAS bf16x8*)(lds + PG8_SA(b, h) + aoff + m * 2048 + k * 1024); } while (0)
; #define PG8_LDB(dst, b, h) do { _Pragma("unroll") for (int n = 0; n < 2; ++n) _Pragma("unroll") for (int k = 0; k < 2; ++k) dst[n][k] = *(const PG8_LAS bf16x8*)(lds + PG8_SB(b, h) + boff + n * 2048 + k * 1024); } while (0)
; #define PG8_MMA(ai, bj, At, Bt) do { __builtin_amdgcn_s_setprio(1); _Pragma("unroll") for (int m = 0; m < 4; ++m) _Pragma("unroll") for (int n = 0; n < 2; ++n) _Pragma("unroll") for (int k = 0; k < 2; ++k) \
;         mma1<I8>(acc[ai][bj][m][n], Bt[n][k], At[m][k]); __builtin_amdgcn_s_setprio(0); } while (0)
; #define PG8_WAIT_V(n) asm volatile("s_waitcnt vmcnt(" #n ")" ::: "memory")
; #define PG8_WAIT_L(n) asm volatile("s_waitcnt lgkmcnt(" #n ")" ::: "memory")
; #define PG8_BAR __builtin_amdgcn_s_barrier()
; #define PG8_SCHED __builtin_amdgcn_sched_barrier(0)
; template <class Epi, class Sched, bool ALIGN_EPI = false, bool SP2 = false, bool I8 = false>
; __device__ __forceinline__ void gemm_phase(PG8_LAS unsigned char* lds, const Gemm g, const Sched& S, const Epi& E, const int tid) {
;     ...
;         for (int t = 0; t < nt; t += 2) {
;             const bool last = (t == nt - 2);
;             const char* a1 = cA + (size_t)(t + 1) * kstep;
;             const char* a2 = last ? nA : cA + (size_t)(t + 2) * kstep; const char* b2 = last ? nB : cB + (size_t)(t + 2) * kstep;
;             const char* a3 = a2 + kstep; const char* b3 = b2 + kstep;
;             if (last && has_next) S.a_ready(nxt);
;             if constexpr (SP2) {
;             PG8_LDB(B0, 0, 0); PG8_LDB(B1, 0, 1); PG8_SCHED; PG8_LDA(At, 0, 0); PG8_STAGE(PG8_SA(1, 1), a1 + hstepA, voffA);
;             PG8_WAIT_V(8); PG8_WAIT_L(0); PG8_BAR; PG8_MMA(0, 0, At, B0); PG8_MMA(0, 1, At, B1); PG8_BAR; PG8_SCHED;
;             PG8_LDA(At, 0, 1); PG8_STAGE(PG8_SB(0, 0), b2, voffB); PG8_STAGE(PG8_SB(0, 1), b2 + hstepB, voffB); PG8_STAGE(PG8_SA(0, 0), a2, voffA);
.LBB0_1009:
	s_add_u32 s8, s6, 0xfff80080
	s_addc_u32 s9, s7, -1
	s_add_i32 s54, 0, 0x10000
	s_cmp_eq_u32 s49, 28
	s_cselect_b32 s13, s11, s9
	s_cselect_b32 s12, s14, s8
	v_add_u32_e32 v96, s54, v243
	s_cselect_b32 s9, s15, s41
	s_cselect_b32 s8, s24, s25
	s_add_i32 s56, 0, 0x14000
	ds_read_b128 v[130:133], v96
	ds_read_b128 v[134:137], v96 offset:1024
	ds_read_b128 v[138:141], v96 offset:2048
	ds_read_b128 v[142:145], v96 offset:3072
	v_add_u32_e32 v96, s56, v243
	ds_read_b128 v[150:153], v96
	ds_read_b128 v[162:165], v96 offset:1024
	ds_read_b128 v[166:169], v96 offset:2048
	ds_read_b128 v[170:173], v96 offset:3072
	v_lshl_add_u64 v[194:195], s[6:7], 0, v[148:149]
	s_add_i32 m0, s93, 0xc000
	ds_read_b128 v[174:177], v244
	ds_read_b128 v[178:181], v244 offset:1024
	ds_read_b128 v[182:185], v244 offset:2048
	ds_read_b128 v[186:189], v244 offset:3072
	ds_read_b128 v[190:193], v244 offset:4096
	ds_read_b128 v[200:203], v244 offset:5120
	ds_read_b128 v[204:207], v244 offset:6144
	ds_read_b128 v[208:211], v244 offset:7168
	global_load_lds_dwordx4 v[194:195], off
	v_lshl_add_u64 v[194:195], s[6:7], 0, v[146:147]
	s_add_i32 m0, s93, 0xe000
	s_nop 0
	global_load_lds_dwordx4 v[194:195], off
	s_waitcnt vmcnt(8)
	s_waitcnt lgkmcnt(0)
	s_setprio 1
	s_barrier
	v_mfma_i32_16x16x64_i8 v[126:129], v[130:133], v[174:177], v[126:129]
	v_mfma_i32_16x16x64_i8 v[122:125], v[138:141], v[174:177], v[122:125]
	v_mfma_i32_16x16x64_i8 v[110:113], v[130:133], v[182:185], v[110:113]
	v_mfma_i32_16x16x64_i8 v[106:109], v[138:141], v[182:185], v[106:109]
	v_mfma_i32_16x16x64_i8 v[92:95], v[130:133], v[190:193], v[92:95]
	v_mfma_i32_16x16x64_i8 v[88:91], v[138:141], v[190:193], v[88:91]
	v_mfma_i32_16x16x64_i8 v[76:79], v[130:133], v[204:207], v[76:79]
	v_mfma_i32_16x16x64_i8 v[72:75], v[138:141], v[204:207], v[72:75]
	v_mfma_i32_16x16x64_i8 v[126:129], v[134:137], v[178:181], v[126:129]
	v_mfma_i32_16x16x64_i8 v[122:125], v[142:145], v[178:181], v[122:125]
	v_mfma_i32_16x16x64_i8 v[110:113], v[134:137], v[186:189], v[110:113]
	v_mfma_i32_16x16x64_i8 v[106:109], v[142:145], v[186:189], v[106:109]
	v_mfma_i32_16x16x64_i8 v[92:95], v[134:137], v[200:203], v[92:95]
	v_mfma_i32_16x16x64_i8 v[88:91], v[142:145], v[200:203], v[88:91]
	v_mfma_i32_16x16x64_i8 v[76:79], v[134:137], v[208:211], v[76:79]
	v_mfma_i32_16x16x64_i8 v[72:75], v[142:145], v[208:211], v[72:75]
	v_mfma_i32_16x16x64_i8 v[118:121], v[150:153], v[174:177], v[118:121]
	v_mfma_i32_16x16x64_i8 v[114:117], v[166:169], v[174:177], v[114:117]
	v_mfma_i32_16x16x64_i8 v[102:105], v[150:153], v[182:185], v[102:105]
	v_mfma_i32_16x16x64_i8 v[98:101], v[166:169], v[182:185], v[98:101]
	v_mfma_i32_16x16x64_i8 v[84:87], v[150:153], v[190:193], v[84:87]
	v_mfma_i32_16x16x64_i8 v[80:83], v[166:169], v[190:193], v[80:83]
	v_mfma_i32_16x16x64_i8 v[68:71], v[150:153], v[204:207], v[68:71]
	v_mfma_i32_16x16x64_i8 v[64:67], v[166:169], v[204:207], v[64:67]
	v_mfma_i32_16x16x64_i8 v[118:121], v[162:165], v[178:181], v[118:121]
	v_mfma_i32_16x16x64_i8 v[114:117], v[170:173], v[178:181], v[114:117]
	v_mfma_i32_16x16x64_i8 v[102:105], v[162:165], v[186:189], v[102:105]
	v_mfma_i32_16x16x64_i8 v[98:101], v[170:173], v[186:189], v[98:101]
	v_mfma_i32_16x16x64_i8 v[84:87], v[162:165], v[200:203], v[84:87]
	v_mfma_i32_16x16x64_i8 v[80:83], v[170:173], v[200:203], v[80:83]
	v_mfma_i32_16x16x64_i8 v[68:71], v[162:165], v[208:211], v[68:71]
	v_mfma_i32_16x16x64_i8 v[64:67], v[170:173], v[208:211], v[64:67]
	s_barrier
	s_setprio 0
	s_add_i32 s54, s54, s19
	v_lshl_add_u64 v[194:195], s[8:9], 0, v[156:157]
	s_mov_b32 m0, s54
	ds_read_b128 v[174:177], v244 offset:16384
	ds_read_b128 v[178:181], v244 offset:17408
	ds_read_b128 v[182:185], v244 offset:18432
	ds_read_b128 v[186:189], v244 offset:19456
	ds_read_b128 v[190:193], v244 offset:20480
	ds_read_b128 v[200:203], v244 offset:21504
	ds_read_b128 v[204:207], v244 offset:22528
	ds_read_b128 v[208:211], v244 offset:23552
	global_load_lds_dwordx4 v[194:195], off
	s_add_i32 m0, s54, 0x2000
	s_add_u32 s54, s8, 0x80000
	v_lshl_add_u64 v[212:213], s[8:9], 0, v[160:161]
	s_addc_u32 s55, s9, 0
	s_add_i32 s56, s56, s19
	global_load_lds_dwordx4 v[212:213], off
	v_lshl_add_u64 v[214:215], s[54:55], 0, v[156:157]
	s_mov_b32 m0, s56
	v_lshl_add_u64 v[216:217], s[12:13], 0, v[158:159]
	global_load_lds_dwordx4 v[214:215], off
	v_lshl_add_u64 v[214:215], s[54:55], 0, v[160:161]
	s_add_i32 m0, s56, 0x2000
	s_nop 0
	global_load_lds_dwordx4 v[214:215], off
	v_lshl_add_u64 v[214:215], s[12:13], 0, v[154:155]
	s_mov_b32 m0, s93
	s_nop 0
	global_load_lds_dwordx4 v[214:215], off
	s_mov_b32 m0, s66
	s_nop 0
	global_load_lds_dwordx4 v[216:217], off
	s_waitcnt vmcnt(8)
	s_waitcnt lgkmcnt(0)
	s_setprio 1
	s_barrier
; #define PG8_STAGE(bufoff, gbase, voff) do { _Pragma("unroll") for (int _i = 0; _i < 2; ++_i) \
;         __builtin_amdgcn_global_load_lds((const unsigned*)((const char*)(gbase) + (voff)[_i]), (PG8_LAS unsigned*)(lds + (bufoff) + ldsw + _i * 8192), 16, 0, 0); } while (0)
; #define PG8_LDA(dst, b, h) do { _Pragma("unroll") for (int m = 0; m < 4; ++m) _Pragma("unroll") for (int k = 0; k < 2; ++k) dst[m][k] = *(const PG8_LAS bf16x8*)(lds + PG8_SA(b, h) + aoff + m * 2048 + k * 1024); } while (0)
; #define PG8_LDB(dst, b, h) do { _Pragma("unroll") for (int n = 0; n < 2; ++n) _Pragma("unroll") for (int k = 0; k < 2; ++k) dst[n][k] = *(const PG8_LAS bf16x8*)(lds + PG8_SB(b, h) + boff + n * 2048 + k * 1024); } while (0)
; #define PG8_MMA(ai, bj, At, Bt) do { __builtin_amdgcn_s_setprio(1); _Pragma("unroll") for (int m = 0; m < 4; ++m) _Pragma("unroll") for (int n = 0; n < 2; ++n) _Pragma("unroll") for (int k = 0; k < 2; ++k) \
;         mma1<I8>(acc[ai][bj][m][n], Bt[n][k], At[m][k]); __builtin_amdgcn_s_setprio(0); } while (0)
; #define PG8_WAIT_V(n) asm volatile("s_waitcnt vmcnt(" #n ")" ::: "memory")
; #define PG8_WAIT_L(n) asm volatile("s_waitcnt lgkmcnt(" #n ")" ::: "memory")
; #define PG8_BAR __builtin_amdgcn_s_barrier()
; #define PG8_SCHED __builtin_amdgcn_sched_barrier(0)
; template <class Epi, class Sched, bool ALIGN_EPI = false, bool SP2 = false, bool I8 = false>
; __device__ __forceinline__ void gemm_phase(PG8_LAS unsigned char* lds, const Gemm g, const Sched& S, const Epi& E, const int tid) {
;     ...
;             PG8_WAIT_V(8); PG8_WAIT_L(0); PG8_BAR; PG8_MMA(1, 0, At, B0); PG8_MMA(1, 1, At, B1); PG8_BAR; PG8_SCHED;
;             PG8_LDB(B0, 1, 0); PG8_LDB(B1, 1, 1); PG8_SCHED; PG8_LDA(At, 1, 0); PG8_STAGE(PG8_SA(0, 1), a2 + hstepA, voffA);
;             PG8_WAIT_V(8); PG8_WAIT_L(0); PG8_BAR; PG8_MMA(0, 0, At, B0); PG8_MMA(0, 1, At, B1); PG8_BAR; PG8_SCHED;
	v_mfma_i32_16x16x64_i8 v[60:63], v[130:133], v[174:177], v[60:63]
	v_mfma_i32_16x16x64_i8 v[56:59], v[138:141], v[174:177], v[56:59]
	v_mfma_i32_16x16x64_i8 v[44:47], v[130:133], v[182:185], v[44:47]
	v_mfma_i32_16x16x64_i8 v[40:43], v[138:141], v[182:185], v[40:43]
	v_mfma_i32_16x16x64_i8 v[28:31], v[130:133], v[190:193], v[28:31]
	v_mfma_i32_16x16x64_i8 v[24:27], v[138:141], v[190:193], v[24:27]
	v_mfma_i32_16x16x64_i8 v[12:15], v[130:133], v[204:207], v[12:15]
	v_mfma_i32_16x16x64_i8 v[8:11], v[138:141], v[204:207], v[8:11]
	v_mfma_i32_16x16x64_i8 v[60:63], v[134:137], v[178:181], v[60:63]
	v_mfma_i32_16x16x64_i8 v[56:59], v[142:145], v[178:181], v[56:59]
	v_mfma_i32_16x16x64_i8 v[44:47], v[134:137], v[186:189], v[44:47]
	v_mfma_i32_16x16x64_i8 v[40:43], v[142:145], v[186:189], v[40:43]
	v_mfma_i32_16x16x64_i8 v[28:31], v[134:137], v[200:203], v[28:31]
	v_mfma_i32_16x16x64_i8 v[24:27], v[142:145], v[200:203], v[24:27]
	v_mfma_i32_16x16x64_i8 v[12:15], v[134:137], v[208:211], v[12:15]
	v_mfma_i32_16x16x64_i8 v[8:11], v[142:145], v[208:211], v[8:11]
	v_mfma_i32_16x16x64_i8 v[52:55], v[150:153], v[174:177], v[52:55]
	v_mfma_i32_16x16x64_i8 v[48:51], v[166:169], v[174:177], v[48:51]
	v_mfma_i32_16x16x64_i8 v[36:39], v[150:153], v[182:185], v[36:39]
	v_mfma_i32_16x16x64_i8 v[32:35], v[166:169], v[182:185], v[32:35]
	v_mfma_i32_16x16x64_i8 v[20:23], v[150:153], v[190:193], v[20:23]
	v_mfma_i32_16x16x64_i8 v[16:19], v[166:169], v[190:193], v[16:19]
	v_mfma_i32_16x16x64_i8 v[4:7], v[150:153], v[204:207], v[4:7]
	v_mfma_i32_16x16x64_i8 v[0:3], v[166:169], v[204:207], v[0:3]
	v_mfma_i32_16x16x64_i8 v[52:55], v[162:165], v[178:181], v[52:55]
	v_mfma_i32_16x16x64_i8 v[48:51], v[170:173], v[178:181], v[48:51]
	v_mfma_i32_16x16x64_i8 v[36:39], v[162:165], v[186:189], v[36:39]
	v_mfma_i32_16x16x64_i8 v[32:35], v[170:173], v[186:189], v[32:35]
	v_mfma_i32_16x16x64_i8 v[20:23], v[162:165], v[200:203], v[20:23]
	v_mfma_i32_16x16x64_i8 v[16:19], v[170:173], v[200:203], v[16:19]
	v_mfma_i32_16x16x64_i8 v[4:7], v[162:165], v[208:211], v[4:7]
	v_mfma_i32_16x16x64_i8 v[0:3], v[170:173], v[208:211], v[0:3]
	s_barrier
	s_setprio 0
	s_add_i32 s54, 0, 0x18000
	v_add_u32_e32 v96, s54, v243
	s_add_i32 s55, 0, 0x1c000
	ds_read_b128 v[130:133], v96
	ds_read_b128 v[134:137], v96 offset:1024
	ds_read_b128 v[138:141], v96 offset:2048
	ds_read_b128 v[142:145], v96 offset:3072
	v_add_u32_e32 v96, s55, v243
	ds_read_b128 v[150:153], v96
	ds_read_b128 v[162:165], v96 offset:1024
	ds_read_b128 v[166:169], v96 offset:2048
	ds_read_b128 v[170:173], v96 offset:3072
	s_add_u32 s12, s12, 0x80000
	s_addc_u32 s13, s13, 0
	s_mov_b32 m0, s1
	v_lshl_add_u64 v[218:219], s[12:13], 0, v[154:155]
	ds_read_b128 v[174:177], v244 offset:32768
	ds_read_b128 v[178:181], v244 offset:33792
	ds_read_b128 v[182:185], v244 offset:34816
	ds_read_b128 v[186:189], v244 offset:35840
	ds_read_b128 v[190:193], v244 offset:36864
	ds_read_b128 v[200:203], v244 offset:37888
	ds_read_b128 v[204:207], v244 offset:38912
	ds_read_b128 v[208:211], v244 offset:39936
	global_load_lds_dwordx4 v[218:219], off
	v_lshl_add_u64 v[218:219], s[12:13], 0, v[158:159]
	s_mov_b32 m0, s52
	s_nop 0
	global_load_lds_dwordx4 v[218:219], off
	s_waitcnt vmcnt(8)
	s_waitcnt lgkmcnt(0)
	s_setprio 1
	s_barrier
	v_mfma_i32_16x16x64_i8 v[126:129], v[130:133], v[174:177], v[126:129]
	v_mfma_i32_16x16x64_i8 v[122:125], v[138:141], v[174:177], v[122:125]
	v_mfma_i32_16x16x64_i8 v[110:113], v[130:133], v[182:185], v[110:113]
	v_mfma_i32_16x16x64_i8 v[106:109], v[138:141], v[182:185], v[106:109]
	v_mfma_i32_16x16x64_i8 v[92:95], v[130:133], v[190:193], v[92:95]
	v_mfma_i32_16x16x64_i8 v[88:91], v[138:141], v[190:193], v[88:91]
	v_mfma_i32_16x16x64_i8 v[76:79], v[130:133], v[204:207], v[76:79]
	v_mfma_i32_16x16x64_i8 v[72:75], v[138:141], v[204:207], v[72:75]
	v_mfma_i32_16x16x64_i8 v[126:129], v[134:137], v[178:181], v[126:129]
	v_mfma_i32_16x16x64_i8 v[122:125], v[142:145], v[178:181], v[122:125]
	v_mfma_i32_16x16x64_i8 v[110:113], v[134:137], v[186:189], v[110:113]
	v_mfma_i32_16x16x64_i8 v[106:109], v[142:145], v[186:189], v[106:109]
	v_mfma_i32_16x16x64_i8 v[92:95], v[134:137], v[200:203], v[92:95]
	v_mfma_i32_16x16x64_i8 v[88:91], v[142:145], v[200:203], v[88:91]
	v_mfma_i32_16x16x64_i8 v[76:79], v[134:137], v[208:211], v[76:79]
	v_mfma_i32_16x16x64_i8 v[72:75], v[142:145], v[208:211], v[72:75]
	v_mfma_i32_16x16x64_i8 v[118:121], v[150:153], v[174:177], v[118:121]
	v_mfma_i32_16x16x64_i8 v[114:117], v[166:169], v[174:177], v[114:117]
	v_mfma_i32_16x16x64_i8 v[102:105], v[150:153], v[182:185], v[102:105]
	v_mfma_i32_16x16x64_i8 v[98:101], v[166:169], v[182:185], v[98:101]
	v_mfma_i32_16x16x64_i8 v[84:87], v[150:153], v[190:193], v[84:87]
	v_mfma_i32_16x16x64_i8 v[80:83], v[166:169], v[190:193], v[80:83]
	v_mfma_i32_16x16x64_i8 v[68:71], v[150:153], v[204:207], v[68:71]
	v_mfma_i32_16x16x64_i8 v[64:67], v[166:169], v[204:207], v[64:67]
	v_mfma_i32_16x16x64_i8 v[118:121], v[162:165], v[178:181], v[118:121]
	v_mfma_i32_16x16x64_i8 v[114:117], v[170:173], v[178:181], v[114:117]
	v_mfma_i32_16x16x64_i8 v[102:105], v[162:165], v[186:189], v[102:105]
	v_mfma_i32_16x16x64_i8 v[98:101], v[170:173], v[186:189], v[98:101]
	v_mfma_i32_16x16x64_i8 v[84:87], v[162:165], v[200:203], v[84:87]
	v_mfma_i32_16x16x64_i8 v[80:83], v[170:173], v[200:203], v[80:83]
	v_mfma_i32_16x16x64_i8 v[68:71], v[162:165], v[208:211], v[68:71]
	v_mfma_i32_16x16x64_i8 v[64:67], v[170:173], v[208:211], v[64:67]
	s_barrier
; #define PG8_STAGE(bufoff, gbase, voff) do { _Pragma("unroll") for (int _i = 0; _i < 2; ++_i) \
;         __builtin_amdgcn_global_load_lds((const unsigned*)((const char*)(gbase) + (voff)[_i]), (PG8_LAS unsigned*)(lds + (bufoff) + ldsw + _i * 8192), 16, 0, 0); } while (0)
; #define PG8_LDA(dst, b, h) do { _Pragma("unroll") for (int m = 0; m < 4; ++m) _Pragma("unroll") for (int k = 0; k < 2; ++k) dst[m][k] = *(const PG8_LAS bf16x8*)(lds + PG8_SA(b, h) + aoff + m * 2048 + k * 1024); } while (0)
; #define PG8_MMA(ai, bj, At, Bt) do { __builtin_amdgcn_s_setprio(1); _Pragma("unroll") for (int m = 0; m < 4; ++m) _Pragma("unroll") for (int n = 0; n < 2; ++n) _Pragma("unroll") for (int k = 0; k < 2; ++k) \
;         mma1<I8>(acc[ai][bj][m][n], Bt[n][k], At[m][k]); __builtin_amdgcn_s_setprio(0); } while (0)
; #define PG8_WAIT_V(n) asm volatile("s_waitcnt vmcnt(" #n ")" ::: "memory")
; #define PG8_WAIT_L(n) asm volatile("s_waitcnt lgkmcnt(" #n ")" ::: "memory")
; #define PG8_BAR __builtin_amdgcn_s_barrier()
; #define PG8_SCHED __builtin_amdgcn_sched_barrier(0)
; template <class Epi, class Sched, bool ALIGN_EPI = false, bool SP2 = false, bool I8 = false>
; __device__ __forceinline__ void gemm_phase(PG8_LAS unsigned char* lds, const Gemm g, const Sched& S, const Epi& E, const int tid) {
;     ...
;             PG8_LDA(At, 1, 1); PG8_STAGE(PG8_SB(1, 0), b3, voffB); PG8_STAGE(PG8_SB(1, 1), b3 + hstepB, voffB); PG8_STAGE(PG8_SA(1, 0), a3, voffA);
;             PG8_WAIT_V(8); PG8_WAIT_L(0); PG8_BAR; PG8_MMA(1, 0, At, B0); PG8_MMA(1, 1, At, B1); PG8_BAR; PG8_SCHED;
;     ...
;         if constexpr (ALIGN_EPI) { if (wr == 0) PG8_BAR; }
	s_setprio 0
	s_add_i32 s12, s54, s19
	v_lshl_add_u64 v[194:195], v[194:195], 0, s[42:43]
	s_mov_b32 m0, s12
	ds_read_b128 v[174:177], v244 offset:49152
	ds_read_b128 v[178:181], v244 offset:50176
	ds_read_b128 v[182:185], v244 offset:51200
	ds_read_b128 v[186:189], v244 offset:52224
	ds_read_b128 v[190:193], v244 offset:53248
	ds_read_b128 v[200:203], v244 offset:54272
	ds_read_b128 v[204:207], v244 offset:55296
	ds_read_b128 v[208:211], v244 offset:56320
	global_load_lds_dwordx4 v[194:195], off
	s_add_i32 m0, s12, 0x2000
	s_add_u32 s8, s8, 0x80080
	v_lshl_add_u64 v[194:195], v[212:213], 0, s[42:43]
	s_addc_u32 s9, s9, 0
	s_add_i32 s12, s55, s19
	global_load_lds_dwordx4 v[194:195], off
	v_lshl_add_u64 v[194:195], s[8:9], 0, v[156:157]
	s_mov_b32 m0, s12
	s_nop 0
	global_load_lds_dwordx4 v[194:195], off
	v_lshl_add_u64 v[194:195], s[8:9], 0, v[160:161]
	s_add_i32 m0, s12, 0x2000
	s_nop 0
	global_load_lds_dwordx4 v[194:195], off
	v_lshl_add_u64 v[194:195], v[214:215], 0, s[42:43]
	s_mov_b32 m0, s63
	s_nop 0
	global_load_lds_dwordx4 v[194:195], off
	v_lshl_add_u64 v[194:195], v[216:217], 0, s[42:43]
	s_mov_b32 m0, s86
	s_nop 0
	global_load_lds_dwordx4 v[194:195], off
	s_waitcnt vmcnt(8)
	s_waitcnt lgkmcnt(0)
	s_setprio 1
	s_barrier
	v_mfma_i32_16x16x64_i8 v[60:63], v[130:133], v[174:177], v[60:63]
	v_mfma_i32_16x16x64_i8 v[56:59], v[138:141], v[174:177], v[56:59]
	v_mfma_i32_16x16x64_i8 v[44:47], v[130:133], v[182:185], v[44:47]
	v_mfma_i32_16x16x64_i8 v[40:43], v[138:141], v[182:185], v[40:43]
	v_mfma_i32_16x16x64_i8 v[28:31], v[130:133], v[190:193], v[28:31]
	v_mfma_i32_16x16x64_i8 v[24:27], v[138:141], v[190:193], v[24:27]
	v_mfma_i32_16x16x64_i8 v[12:15], v[130:133], v[204:207], v[12:15]
	v_mfma_i32_16x16x64_i8 v[8:11], v[138:141], v[204:207], v[8:11]
	v_mfma_i32_16x16x64_i8 v[60:63], v[134:137], v[178:181], v[60:63]
	v_mfma_i32_16x16x64_i8 v[56:59], v[142:145], v[178:181], v[56:59]
	v_mfma_i32_16x16x64_i8 v[44:47], v[134:137], v[186:189], v[44:47]
	v_mfma_i32_16x16x64_i8 v[40:43], v[142:145], v[186:189], v[40:43]
	v_mfma_i32_16x16x64_i8 v[28:31], v[134:137], v[200:203], v[28:31]
	v_mfma_i32_16x16x64_i8 v[24:27], v[142:145], v[200:203], v[24:27]
	v_mfma_i32_16x16x64_i8 v[12:15], v[134:137], v[208:211], v[12:15]
	v_mfma_i32_16x16x64_i8 v[8:11], v[142:145], v[208:211], v[8:11]
	v_mfma_i32_16x16x64_i8 v[52:55], v[150:153], v[174:177], v[52:55]
	v_mfma_i32_16x16x64_i8 v[48:51], v[166:169], v[174:177], v[48:51]
	v_mfma_i32_16x16x64_i8 v[36:39], v[150:153], v[182:185], v[36:39]
	v_mfma_i32_16x16x64_i8 v[32:35], v[166:169], v[182:185], v[32:35]
	v_mfma_i32_16x16x64_i8 v[20:23], v[150:153], v[190:193], v[20:23]
	v_mfma_i32_16x16x64_i8 v[16:19], v[166:169], v[190:193], v[16:19]
	v_mfma_i32_16x16x64_i8 v[4:7], v[150:153], v[204:207], v[4:7]
	v_mfma_i32_16x16x64_i8 v[0:3], v[166:169], v[204:207], v[0:3]
	v_mfma_i32_16x16x64_i8 v[52:55], v[162:165], v[178:181], v[52:55]
	v_mfma_i32_16x16x64_i8 v[48:51], v[170:173], v[178:181], v[48:51]
	v_mfma_i32_16x16x64_i8 v[36:39], v[162:165], v[186:189], v[36:39]
	v_mfma_i32_16x16x64_i8 v[32:35], v[170:173], v[186:189], v[32:35]
	v_mfma_i32_16x16x64_i8 v[20:23], v[162:165], v[200:203], v[20:23]
	v_mfma_i32_16x16x64_i8 v[16:19], v[170:173], v[200:203], v[16:19]
	v_mfma_i32_16x16x64_i8 v[4:7], v[162:165], v[208:211], v[4:7]
	v_mfma_i32_16x16x64_i8 v[0:3], v[170:173], v[208:211], v[0:3]
	s_barrier
	s_setprio 0
	s_add_i32 s49, s49, 2
	s_add_u32 s25, s25, 0x100
	s_addc_u32 s41, s41, 0
	s_add_u32 s6, s6, 0x100
	s_addc_u32 s7, s7, 0
	s_cmp_gt_u32 s49, 29
	s_cbranch_scc0 .LBB0_1009
	s_and_b64 vcc, exec, s[38:39]
	s_cbranch_vccz .LBB0_1012
	s_barrier
